# GEMM phases: the per-segment s_setprio toggles around each MFMA block replaced by one static priority raise for waves 4-7 at the start of each GEMM phase
# speedup vs baseline: 1.0072x; 1.0072x over previous
; #define LAS __attribute__((address_space(3)))
; __global__ void __launch_bounds__(NWAVES * 64, 2) mk_fwd(Params P) {
;     ...
;         pg8::Gemm g{XN, WIN_T, M, NCOL, D}; pg8::StaticOrder S; S.init(M, NCOL, G, bx);
;         pg8::EpiProj E{QA, KA, VA, QB, KB, VB, (const pg8::f32x2g*)ROPEA, (const pg8::f32x2g*)ROPER, (const pg8::f32x2g*)ROPEC, P.qnw, P.knw, Q8, K8, V8T};
;         pg8::gemm_phase<pg8::EpiProj, pg8::StaticOrder, true, true>((LAS unsigned char*)lds, g, S, E);
.LBB0_229:
	v_readlane_b32 s98, v252, 9
	s_cmp_lt_u32 s98, 4
	s_cbranch_scc1 .Lmy_pr_0
	s_setprio 1

; #define PG8_STAGE(bufoff, gbase, voff) do { _Pragma("unroll") for (int _i = 0; _i < 2; ++_i) \
;         __builtin_amdgcn_global_load_lds((const unsigned*)((const char*)(gbase) + (voff)[_i]), (PG8_LAS unsigned*)(lds + (bufoff) + ldsw + _i * 8192), 16, 0, 0); } while (0)
; #define PG8_LDA(dst, b, h) do { _Pragma("unroll") for (int m = 0; m < 4; ++m) _Pragma("unroll") for (int k = 0; k < 2; ++k) dst[m][k] = *(const PG8_LAS bf16x8*)(lds + PG8_SA(b, h) + aoff + m * 2048 + k * 1024); } while (0)
; #define PG8_LDB(dst, b, h) do { _Pragma("unroll") for (int n = 0; n < 2; ++n) _Pragma("unroll") for (int k = 0; k < 2; ++k) dst[n][k] = *(const PG8_LAS bf16x8*)(lds + PG8_SB(b, h) + boff + n * 2048 + k * 1024); } while (0)
; #define PG8_MMA(ai, bj, At, Bt) do { __builtin_amdgcn_s_setprio(1); _Pragma("unroll") for (int m = 0; m < 4; ++m) _Pragma("unroll") for (int n = 0; n < 2; ++n) _Pragma("unroll") for (int k = 0; k < 2; ++k) \
;         acc[ai][bj][m][n] = __builtin_amdgcn_mfma_f32_16x16x32_bf16(Bt[n][k], At[m][k], acc[ai][bj][m][n], 0, 0, 0); __builtin_amdgcn_s_setprio(0); } while (0)
; #define PG8_WAIT_V(n) asm volatile("s_waitcnt vmcnt(" #n ")" ::: "memory")
; #define PG8_BAR __builtin_amdgcn_s_barrier()
; template <class Epi, class Sched, bool ALIGN_EPI = false, bool SP2 = false>
; __device__ __forceinline__ void gemm_phase(PG8_LAS unsigned char* lds, const Gemm g, const Sched& S, const Epi& E) {
;     ...
;         for (int t = 0; t < nt; t += 2) {
;             const bool last = (t == nt - 2);
;             const char* a1 = cA + (size_t)(t + 1) * kstep;
;             const char* a2 = last ? nA : cA + (size_t)(t + 2) * kstep; const char* b2 = last ? nB : cB + (size_t)(t + 2) * kstep;
;             const char* a3 = a2 + kstep; const char* b3 = b2 + kstep;
;             if (last && has_next) S.a_ready(nxt);
;             if constexpr (SP2) {
;             PG8_LDB(B0, 0, 0); PG8_LDB(B1, 0, 1); PG8_SCHED; PG8_LDA(At, 0, 0); PG8_STAGE(PG8_SA(1, 1), a1 + hstep, voffA);
;             PG8_WAIT_V(8); PG8_WAIT_L(0); PG8_BAR; PG8_MMA(0, 0, At, B0); PG8_MMA(0, 1, At, B1); PG8_BAR; PG8_SCHED;
;             PG8_LDA(At, 0, 1); PG8_STAGE(PG8_SB(0, 0), b2, voffB); PG8_STAGE(PG8_SB(0, 1), b2 + hstep, voffB); PG8_STAGE(PG8_SA(0, 0), a2, voffA);
;             PG8_WAIT_V(8); PG8_WAIT_L(0); PG8_BAR; PG8_MMA(1, 0, At, B0); PG8_MMA(1, 1, At, B1); PG8_BAR; PG8_SCHED;
.LBB0_241:
	ds_read_b128 v[128:131], v207
	ds_read_b128 v[132:135], v207 offset:1024
	ds_read_b128 v[136:139], v207 offset:2048
	ds_read_b128 v[140:143], v207 offset:3072
	s_waitcnt vmcnt(0)
	ds_read_b128 v[144:147], v212
	ds_read_b128 v[148:151], v212 offset:1024
	ds_read_b128 v[152:155], v212 offset:2048
	ds_read_b128 v[156:159], v212 offset:3072
	s_add_u32 s10, s6, 0xfffc0080
	s_addc_u32 s11, s7, -1
	s_cmp_eq_u32 s85, 12
	s_cselect_b32 s15, s9, s11
	s_cselect_b32 s14, s77, s10
	s_cselect_b32 s11, s75, s83
	s_cselect_b32 s10, s84, s82
	v_lshl_add_u64 v[198:199], s[6:7], 0, v[184:185]
	s_add_i32 m0, s13, 0xc000
	ds_read_b128 v[194:197], v208
	ds_read_b128 v[216:219], v208 offset:1024
	ds_read_b128 v[220:223], v208 offset:2048
	ds_read_b128 v[224:227], v208 offset:3072
	ds_read_b128 v[228:231], v208 offset:4096
	ds_read_b128 v[232:235], v208 offset:5120
	ds_read_b128 v[236:239], v208 offset:6144
	ds_read_b128 v[240:243], v208 offset:7168
	global_load_lds_dwordx4 v[198:199], off
	v_lshl_add_u64 v[198:199], s[6:7], 0, v[186:187]
	s_add_i32 m0, s13, 0xe000
	s_nop 0
	global_load_lds_dwordx4 v[198:199], off
	s_waitcnt vmcnt(8)
	s_waitcnt lgkmcnt(0)
	s_barrier
	s_waitcnt lgkmcnt(0)
	v_mfma_f32_16x16x32_bf16 v[120:123], v[128:131], v[194:197], v[120:123]
	v_mfma_f32_16x16x32_bf16 v[124:127], v[136:139], v[194:197], v[124:127]
	v_mfma_f32_16x16x32_bf16 v[104:107], v[128:131], v[220:223], v[104:107]
	v_mfma_f32_16x16x32_bf16 v[108:111], v[136:139], v[220:223], v[108:111]
	v_mfma_f32_16x16x32_bf16 v[88:91], v[128:131], v[228:231], v[88:91]
	v_mfma_f32_16x16x32_bf16 v[92:95], v[136:139], v[228:231], v[92:95]
	v_mfma_f32_16x16x32_bf16 v[72:75], v[128:131], v[236:239], v[72:75]
	v_mfma_f32_16x16x32_bf16 v[76:79], v[136:139], v[236:239], v[76:79]
	v_mfma_f32_16x16x32_bf16 v[120:123], v[132:135], v[216:219], v[120:123]
	v_mfma_f32_16x16x32_bf16 v[124:127], v[140:143], v[216:219], v[124:127]
	v_mfma_f32_16x16x32_bf16 v[104:107], v[132:135], v[224:227], v[104:107]
	v_mfma_f32_16x16x32_bf16 v[108:111], v[140:143], v[224:227], v[108:111]
	v_mfma_f32_16x16x32_bf16 v[88:91], v[132:135], v[232:235], v[88:91]
	v_mfma_f32_16x16x32_bf16 v[92:95], v[140:143], v[232:235], v[92:95]
	v_mfma_f32_16x16x32_bf16 v[72:75], v[132:135], v[240:243], v[72:75]
	v_mfma_f32_16x16x32_bf16 v[76:79], v[140:143], v[240:243], v[76:79]
	v_mfma_f32_16x16x32_bf16 v[112:115], v[144:147], v[194:197], v[112:115]
	v_mfma_f32_16x16x32_bf16 v[116:119], v[152:155], v[194:197], v[116:119]
	v_mfma_f32_16x16x32_bf16 v[96:99], v[144:147], v[220:223], v[96:99]
	v_mfma_f32_16x16x32_bf16 v[100:103], v[152:155], v[220:223], v[100:103]
	v_mfma_f32_16x16x32_bf16 v[80:83], v[144:147], v[228:231], v[80:83]
	v_mfma_f32_16x16x32_bf16 v[84:87], v[152:155], v[228:231], v[84:87]
	v_mfma_f32_16x16x32_bf16 v[64:67], v[144:147], v[236:239], v[64:67]
	v_mfma_f32_16x16x32_bf16 v[68:71], v[152:155], v[236:239], v[68:71]
	v_mfma_f32_16x16x32_bf16 v[112:115], v[148:151], v[216:219], v[112:115]
	v_mfma_f32_16x16x32_bf16 v[116:119], v[156:159], v[216:219], v[116:119]
	v_mfma_f32_16x16x32_bf16 v[96:99], v[148:151], v[224:227], v[96:99]
	v_mfma_f32_16x16x32_bf16 v[100:103], v[156:159], v[224:227], v[100:103]
	v_mfma_f32_16x16x32_bf16 v[80:83], v[148:151], v[232:235], v[80:83]
	v_mfma_f32_16x16x32_bf16 v[84:87], v[156:159], v[232:235], v[84:87]
	v_mfma_f32_16x16x32_bf16 v[64:67], v[148:151], v[240:243], v[64:67]
	v_mfma_f32_16x16x32_bf16 v[68:71], v[156:159], v[240:243], v[68:71]
	s_barrier
	s_add_i32 s87, s63, s12
	v_lshl_add_u64 v[198:199], s[10:11], 0, v[162:163]
	s_mov_b32 m0, s87
	ds_read_b128 v[194:197], v208 offset:16384
	ds_read_b128 v[216:219], v208 offset:17408
	ds_read_b128 v[220:223], v208 offset:18432
	ds_read_b128 v[224:227], v208 offset:19456
	ds_read_b128 v[228:231], v208 offset:20480
	ds_read_b128 v[232:235], v208 offset:21504
	ds_read_b128 v[236:239], v208 offset:22528
	ds_read_b128 v[240:243], v208 offset:23552
	global_load_lds_dwordx4 v[198:199], off
	s_add_i32 m0, s87, 0x2000
	s_add_u32 s88, s10, 0x40000
	v_lshl_add_u64 v[244:245], s[10:11], 0, v[166:167]
	s_addc_u32 s89, s11, 0
	s_add_i32 s87, s68, s12
	global_load_lds_dwordx4 v[244:245], off
	v_lshl_add_u64 v[246:247], s[88:89], 0, v[162:163]
	s_mov_b32 m0, s87
	v_lshl_add_u64 v[248:249], s[14:15], 0, v[164:165]
	global_load_lds_dwordx4 v[246:247], off
	v_lshl_add_u64 v[246:247], s[88:89], 0, v[166:167]
	s_add_i32 m0, s87, 0x2000
	s_nop 0
	global_load_lds_dwordx4 v[246:247], off
	v_lshl_add_u64 v[246:247], s[14:15], 0, v[160:161]
	s_mov_b32 m0, s13
	s_nop 0
	global_load_lds_dwordx4 v[246:247], off
	s_mov_b32 m0, s66
	s_nop 0
	global_load_lds_dwordx4 v[248:249], off
	s_waitcnt vmcnt(8)
	s_waitcnt lgkmcnt(0)
	s_barrier
; #define PG8_STAGE(bufoff, gbase, voff) do { _Pragma("unroll") for (int _i = 0; _i < 2; ++_i) \
;         __builtin_amdgcn_global_load_lds((const unsigned*)((const char*)(gbase) + (voff)[_i]), (PG8_LAS unsigned*)(lds + (bufoff) + ldsw + _i * 8192), 16, 0, 0); } while (0)
; #define PG8_LDA(dst, b, h) do { _Pragma("unroll") for (int m = 0; m < 4; ++m) _Pragma("unroll") for (int k = 0; k < 2; ++k) dst[m][k] = *(const PG8_LAS bf16x8*)(lds + PG8_SA(b, h) + aoff + m * 2048 + k * 1024); } while (0)
; #define PG8_LDB(dst, b, h) do { _Pragma("unroll") for (int n = 0; n < 2; ++n) _Pragma("unroll") for (int k = 0; k < 2; ++k) dst[n][k] = *(const PG8_LAS bf16x8*)(lds + PG8_SB(b, h) + boff + n * 2048 + k * 1024); } while (0)
; #define PG8_MMA(ai, bj, At, Bt) do { __builtin_amdgcn_s_setprio(1); _Pragma("unroll") for (int m = 0; m < 4; ++m) _Pragma("unroll") for (int n = 0; n < 2; ++n) _Pragma("unroll") for (int k = 0; k < 2; ++k) \
;         acc[ai][bj][m][n] = __builtin_amdgcn_mfma_f32_16x16x32_bf16(Bt[n][k], At[m][k], acc[ai][bj][m][n], 0, 0, 0); __builtin_amdgcn_s_setprio(0); } while (0)
; #define PG8_WAIT_V(n) asm volatile("s_waitcnt vmcnt(" #n ")" ::: "memory")
; #define PG8_WAIT_L(n) asm volatile("s_waitcnt lgkmcnt(" #n ")" ::: "memory")
; #define PG8_BAR __builtin_amdgcn_s_barrier()
; #define PG8_SCHED __builtin_amdgcn_sched_barrier(0)
; template <class Epi, class Sched, bool ALIGN_EPI = false, bool SP2 = false>
; __device__ __forceinline__ void gemm_phase(PG8_LAS unsigned char* lds, const Gemm g, const Sched& S, const Epi& E) {
;     ...
;             PG8_WAIT_V(8); PG8_WAIT_L(0); PG8_BAR; PG8_MMA(1, 0, At, B0); PG8_MMA(1, 1, At, B1); PG8_BAR; PG8_SCHED;
;             PG8_LDB(B0, 1, 0); PG8_LDB(B1, 1, 1); PG8_SCHED; PG8_LDA(At, 1, 0); PG8_STAGE(PG8_SA(0, 1), a2 + hstep, voffA);
;             PG8_WAIT_V(8); PG8_WAIT_L(0); PG8_BAR; PG8_MMA(0, 0, At, B0); PG8_MMA(0, 1, At, B1); PG8_BAR; PG8_SCHED;
;             PG8_LDA(At, 1, 1); PG8_STAGE(PG8_SB(1, 0), b3, voffB); PG8_STAGE(PG8_SB(1, 1), b3 + hstep, voffB); PG8_STAGE(PG8_SA(1, 0), a3, voffA);
	s_waitcnt lgkmcnt(0)
	v_mfma_f32_16x16x32_bf16 v[56:59], v[128:131], v[194:197], v[56:59]
	v_mfma_f32_16x16x32_bf16 v[60:63], v[136:139], v[194:197], v[60:63]
	v_mfma_f32_16x16x32_bf16 v[40:43], v[128:131], v[220:223], v[40:43]
	v_mfma_f32_16x16x32_bf16 v[44:47], v[136:139], v[220:223], v[44:47]
	v_mfma_f32_16x16x32_bf16 v[24:27], v[128:131], v[228:231], v[24:27]
	v_mfma_f32_16x16x32_bf16 v[28:31], v[136:139], v[228:231], v[28:31]
	v_mfma_f32_16x16x32_bf16 v[8:11], v[128:131], v[236:239], v[8:11]
	v_mfma_f32_16x16x32_bf16 v[12:15], v[136:139], v[236:239], v[12:15]
	v_mfma_f32_16x16x32_bf16 v[56:59], v[132:135], v[216:219], v[56:59]
	v_mfma_f32_16x16x32_bf16 v[60:63], v[140:143], v[216:219], v[60:63]
	v_mfma_f32_16x16x32_bf16 v[40:43], v[132:135], v[224:227], v[40:43]
	v_mfma_f32_16x16x32_bf16 v[44:47], v[140:143], v[224:227], v[44:47]
	v_mfma_f32_16x16x32_bf16 v[24:27], v[132:135], v[232:235], v[24:27]
	v_mfma_f32_16x16x32_bf16 v[28:31], v[140:143], v[232:235], v[28:31]
	v_mfma_f32_16x16x32_bf16 v[8:11], v[132:135], v[240:243], v[8:11]
	v_mfma_f32_16x16x32_bf16 v[12:15], v[140:143], v[240:243], v[12:15]
	v_mfma_f32_16x16x32_bf16 v[48:51], v[144:147], v[194:197], v[48:51]
	v_mfma_f32_16x16x32_bf16 v[52:55], v[152:155], v[194:197], v[52:55]
	v_mfma_f32_16x16x32_bf16 v[32:35], v[144:147], v[220:223], v[32:35]
	v_mfma_f32_16x16x32_bf16 v[36:39], v[152:155], v[220:223], v[36:39]
	v_mfma_f32_16x16x32_bf16 v[16:19], v[144:147], v[228:231], v[16:19]
	v_mfma_f32_16x16x32_bf16 v[20:23], v[152:155], v[228:231], v[20:23]
	v_mfma_f32_16x16x32_bf16 v[0:3], v[144:147], v[236:239], v[0:3]
	v_mfma_f32_16x16x32_bf16 v[4:7], v[152:155], v[236:239], v[4:7]
	v_mfma_f32_16x16x32_bf16 v[48:51], v[148:151], v[216:219], v[48:51]
	v_mfma_f32_16x16x32_bf16 v[52:55], v[156:159], v[216:219], v[52:55]
	v_mfma_f32_16x16x32_bf16 v[32:35], v[148:151], v[224:227], v[32:35]
	v_mfma_f32_16x16x32_bf16 v[36:39], v[156:159], v[224:227], v[36:39]
	v_mfma_f32_16x16x32_bf16 v[16:19], v[148:151], v[232:235], v[16:19]
	v_mfma_f32_16x16x32_bf16 v[20:23], v[156:159], v[232:235], v[20:23]
	v_mfma_f32_16x16x32_bf16 v[0:3], v[148:151], v[240:243], v[0:3]
	v_mfma_f32_16x16x32_bf16 v[4:7], v[156:159], v[240:243], v[4:7]
	s_barrier
	s_add_i32 s87, 0, 0x18000
	s_add_i32 s88, 0, 0x1c000
	v_add_u32_e32 v140, s87, v181
	v_add_u32_e32 v156, s88, v181
	ds_read_b128 v[128:131], v140
	ds_read_b128 v[132:135], v140 offset:1024
	ds_read_b128 v[136:139], v140 offset:2048
	ds_read_b128 v[140:143], v140 offset:3072
	ds_read_b128 v[144:147], v156
	ds_read_b128 v[148:151], v156 offset:1024
	ds_read_b128 v[152:155], v156 offset:2048
	ds_read_b128 v[156:159], v156 offset:3072
	s_add_u32 s14, s14, 0x40000
	s_addc_u32 s15, s15, 0
	s_mov_b32 m0, s67
	v_lshl_add_u64 v[250:251], s[14:15], 0, v[160:161]
	ds_read_b128 v[194:197], v208 offset:32768
	ds_read_b128 v[216:219], v208 offset:33792
	ds_read_b128 v[220:223], v208 offset:34816
	ds_read_b128 v[224:227], v208 offset:35840
	ds_read_b128 v[228:231], v208 offset:36864
	ds_read_b128 v[232:235], v208 offset:37888
	ds_read_b128 v[236:239], v208 offset:38912
	ds_read_b128 v[240:243], v208 offset:39936
	global_load_lds_dwordx4 v[250:251], off
	v_lshl_add_u64 v[250:251], s[14:15], 0, v[164:165]
	s_mov_b32 m0, s33
	s_nop 0
	global_load_lds_dwordx4 v[250:251], off
	s_waitcnt vmcnt(8)
	s_waitcnt lgkmcnt(0)
	s_barrier
	s_waitcnt lgkmcnt(0)
	v_mfma_f32_16x16x32_bf16 v[120:123], v[128:131], v[194:197], v[120:123]
	v_mfma_f32_16x16x32_bf16 v[124:127], v[136:139], v[194:197], v[124:127]
	v_mfma_f32_16x16x32_bf16 v[104:107], v[128:131], v[220:223], v[104:107]
	v_mfma_f32_16x16x32_bf16 v[108:111], v[136:139], v[220:223], v[108:111]
	v_mfma_f32_16x16x32_bf16 v[88:91], v[128:131], v[228:231], v[88:91]
	v_mfma_f32_16x16x32_bf16 v[92:95], v[136:139], v[228:231], v[92:95]
	v_mfma_f32_16x16x32_bf16 v[72:75], v[128:131], v[236:239], v[72:75]
	v_mfma_f32_16x16x32_bf16 v[76:79], v[136:139], v[236:239], v[76:79]
	v_mfma_f32_16x16x32_bf16 v[120:123], v[132:135], v[216:219], v[120:123]
	v_mfma_f32_16x16x32_bf16 v[124:127], v[140:143], v[216:219], v[124:127]
	v_mfma_f32_16x16x32_bf16 v[104:107], v[132:135], v[224:227], v[104:107]
	v_mfma_f32_16x16x32_bf16 v[108:111], v[140:143], v[224:227], v[108:111]
	v_mfma_f32_16x16x32_bf16 v[88:91], v[132:135], v[232:235], v[88:91]
	v_mfma_f32_16x16x32_bf16 v[92:95], v[140:143], v[232:235], v[92:95]
	v_mfma_f32_16x16x32_bf16 v[72:75], v[132:135], v[240:243], v[72:75]
	v_mfma_f32_16x16x32_bf16 v[76:79], v[140:143], v[240:243], v[76:79]
	v_mfma_f32_16x16x32_bf16 v[112:115], v[144:147], v[194:197], v[112:115]
	v_mfma_f32_16x16x32_bf16 v[116:119], v[152:155], v[194:197], v[116:119]
	v_mfma_f32_16x16x32_bf16 v[96:99], v[144:147], v[220:223], v[96:99]
	v_mfma_f32_16x16x32_bf16 v[100:103], v[152:155], v[220:223], v[100:103]
	v_mfma_f32_16x16x32_bf16 v[80:83], v[144:147], v[228:231], v[80:83]
	v_mfma_f32_16x16x32_bf16 v[84:87], v[152:155], v[228:231], v[84:87]
	v_mfma_f32_16x16x32_bf16 v[64:67], v[144:147], v[236:239], v[64:67]
	v_mfma_f32_16x16x32_bf16 v[68:71], v[152:155], v[236:239], v[68:71]
	v_mfma_f32_16x16x32_bf16 v[112:115], v[148:151], v[216:219], v[112:115]
	v_mfma_f32_16x16x32_bf16 v[116:119], v[156:159], v[216:219], v[116:119]
	v_mfma_f32_16x16x32_bf16 v[96:99], v[148:151], v[224:227], v[96:99]
	v_mfma_f32_16x16x32_bf16 v[100:103], v[156:159], v[224:227], v[100:103]
	v_mfma_f32_16x16x32_bf16 v[80:83], v[148:151], v[232:235], v[80:83]
	v_mfma_f32_16x16x32_bf16 v[84:87], v[156:159], v[232:235], v[84:87]
	v_mfma_f32_16x16x32_bf16 v[64:67], v[148:151], v[240:243], v[64:67]
	v_mfma_f32_16x16x32_bf16 v[68:71], v[156:159], v[240:243], v[68:71]
	s_barrier
; #define PG8_STAGE(bufoff, gbase, voff) do { _Pragma("unroll") for (int _i = 0; _i < 2; ++_i) \
;         __builtin_amdgcn_global_load_lds((const unsigned*)((const char*)(gbase) + (voff)[_i]), (PG8_LAS unsigned*)(lds + (bufoff) + ldsw + _i * 8192), 16, 0, 0); } while (0)
; #define PG8_LDA(dst, b, h) do { _Pragma("unroll") for (int m = 0; m < 4; ++m) _Pragma("unroll") for (int k = 0; k < 2; ++k) dst[m][k] = *(const PG8_LAS bf16x8*)(lds + PG8_SA(b, h) + aoff + m * 2048 + k * 1024); } while (0)
; #define PG8_WAIT_V(n) asm volatile("s_waitcnt vmcnt(" #n ")" ::: "memory")
; template <class Epi, class Sched, bool ALIGN_EPI = false, bool SP2 = false>
; __device__ __forceinline__ void gemm_phase(PG8_LAS unsigned char* lds, const Gemm g, const Sched& S, const Epi& E) {
;     ...
;             PG8_LDA(At, 1, 1); PG8_STAGE(PG8_SB(1, 0), b3, voffB); PG8_STAGE(PG8_SB(1, 1), b3 + hstep, voffB); PG8_STAGE(PG8_SA(1, 0), a3, voffA);
;             PG8_WAIT_V(8); PG8_WAIT_L(0); PG8_BAR; PG8_MMA(1, 0, At, B0); PG8_MMA(1, 1, At, B1); PG8_BAR; PG8_SCHED;
;             } else {
;             PG8_LDB(B0, 0, 0); PG8_SCHED; PG8_LDA(At, 0, 0); PG8_STAGE(PG8_SA(1, 1), a1 + hstep, voffA);
;             PG8_WAIT_L(8); PG8_BAR; PG8_WAIT_L(0); PG8_MMA(0, 0, At, B0); PG8_BAR; PG8_SCHED;
;             PG8_LDB(B1, 0, 1); PG8_STAGE(PG8_SB(0, 0), b2, voffB);
;             PG8_BAR; PG8_WAIT_L(0); PG8_MMA(0, 1, At, B1); PG8_BAR;
;             PG8_LDA(At, 0, 1); PG8_STAGE(PG8_SA(0, 0), a2, voffA);
;             PG8_BAR; PG8_WAIT_L(0); PG8_MMA(1, 0, At, B0); PG8_BAR; PG8_SCHED;
;             PG8_STAGE(PG8_SB(0, 1), b2 + hstep, voffB);
;             PG8_WAIT_V(6); PG8_BAR; PG8_MMA(1, 1, At, B1); PG8_BAR;
;             PG8_LDB(B0, 1, 0); PG8_SCHED; PG8_LDA(At, 1, 0); PG8_STAGE(PG8_SA(0, 1), a2 + hstep, voffA);
;             PG8_WAIT_L(8); PG8_BAR; PG8_WAIT_L(0); PG8_MMA(0, 0, At, B0); PG8_BAR; PG8_SCHED;
;             PG8_LDB(B1, 1, 1); PG8_STAGE(PG8_SB(1, 0), b3, voffB);
;             PG8_BAR; PG8_WAIT_L(0); PG8_MMA(0, 1, At, B1); PG8_BAR;
;             PG8_LDA(At, 1, 1); PG8_STAGE(PG8_SA(1, 0), a3, voffA);
;             PG8_BAR; PG8_WAIT_L(0); PG8_MMA(1, 0, At, B0); PG8_BAR; PG8_SCHED;
;             PG8_STAGE(PG8_SB(1, 1), b3 + hstep, voffB);
;             PG8_WAIT_V(6); PG8_BAR; PG8_MMA(1, 1, At, B1); PG8_BAR;
;             }
;         }
;         if constexpr (ALIGN_EPI) { if (wr == 0) PG8_BAR; }
	s_add_i32 s14, s87, s12
	v_lshl_add_u64 v[198:199], v[198:199], 0, s[44:45]
	s_mov_b32 m0, s14
	ds_read_b128 v[194:197], v208 offset:49152
	ds_read_b128 v[216:219], v208 offset:50176
	ds_read_b128 v[220:223], v208 offset:51200
	ds_read_b128 v[224:227], v208 offset:52224
	ds_read_b128 v[228:231], v208 offset:53248
	ds_read_b128 v[232:235], v208 offset:54272
	ds_read_b128 v[236:239], v208 offset:55296
	ds_read_b128 v[240:243], v208 offset:56320
	global_load_lds_dwordx4 v[198:199], off
	s_add_i32 m0, s14, 0x2000
	s_add_u32 s10, s10, 0x40080
	v_lshl_add_u64 v[198:199], v[244:245], 0, s[44:45]
	s_addc_u32 s11, s11, 0
	s_add_i32 s14, s88, s12
	global_load_lds_dwordx4 v[198:199], off
	v_lshl_add_u64 v[198:199], s[10:11], 0, v[162:163]
	s_mov_b32 m0, s14
	s_nop 0
	global_load_lds_dwordx4 v[198:199], off
	v_lshl_add_u64 v[198:199], s[10:11], 0, v[166:167]
	s_add_i32 m0, s14, 0x2000
	s_nop 0
	global_load_lds_dwordx4 v[198:199], off
	v_lshl_add_u64 v[198:199], v[246:247], 0, s[44:45]
	s_mov_b32 m0, s52
	s_nop 0
	global_load_lds_dwordx4 v[198:199], off
	v_lshl_add_u64 v[198:199], v[248:249], 0, s[44:45]
	s_mov_b32 m0, s53
	s_nop 0
	global_load_lds_dwordx4 v[198:199], off
	s_waitcnt vmcnt(8)
	s_waitcnt lgkmcnt(0)
	s_barrier
	s_waitcnt lgkmcnt(0)
	v_mfma_f32_16x16x32_bf16 v[56:59], v[128:131], v[194:197], v[56:59]
	v_mfma_f32_16x16x32_bf16 v[60:63], v[136:139], v[194:197], v[60:63]
	v_mfma_f32_16x16x32_bf16 v[40:43], v[128:131], v[220:223], v[40:43]
	v_mfma_f32_16x16x32_bf16 v[44:47], v[136:139], v[220:223], v[44:47]
	v_mfma_f32_16x16x32_bf16 v[24:27], v[128:131], v[228:231], v[24:27]
	v_mfma_f32_16x16x32_bf16 v[28:31], v[136:139], v[228:231], v[28:31]
	v_mfma_f32_16x16x32_bf16 v[8:11], v[128:131], v[236:239], v[8:11]
	v_mfma_f32_16x16x32_bf16 v[12:15], v[136:139], v[236:239], v[12:15]
	v_mfma_f32_16x16x32_bf16 v[56:59], v[132:135], v[216:219], v[56:59]
	v_mfma_f32_16x16x32_bf16 v[60:63], v[140:143], v[216:219], v[60:63]
	v_mfma_f32_16x16x32_bf16 v[40:43], v[132:135], v[224:227], v[40:43]
	v_mfma_f32_16x16x32_bf16 v[44:47], v[140:143], v[224:227], v[44:47]
	v_mfma_f32_16x16x32_bf16 v[24:27], v[132:135], v[232:235], v[24:27]
	v_mfma_f32_16x16x32_bf16 v[28:31], v[140:143], v[232:235], v[28:31]
	v_mfma_f32_16x16x32_bf16 v[8:11], v[132:135], v[240:243], v[8:11]
	v_mfma_f32_16x16x32_bf16 v[12:15], v[140:143], v[240:243], v[12:15]
	v_mfma_f32_16x16x32_bf16 v[48:51], v[144:147], v[194:197], v[48:51]
	v_mfma_f32_16x16x32_bf16 v[52:55], v[152:155], v[194:197], v[52:55]
	v_mfma_f32_16x16x32_bf16 v[32:35], v[144:147], v[220:223], v[32:35]
	v_mfma_f32_16x16x32_bf16 v[36:39], v[152:155], v[220:223], v[36:39]
	v_mfma_f32_16x16x32_bf16 v[16:19], v[144:147], v[228:231], v[16:19]
	v_mfma_f32_16x16x32_bf16 v[20:23], v[152:155], v[228:231], v[20:23]
	v_mfma_f32_16x16x32_bf16 v[0:3], v[144:147], v[236:239], v[0:3]
	v_mfma_f32_16x16x32_bf16 v[4:7], v[152:155], v[236:239], v[4:7]
	v_mfma_f32_16x16x32_bf16 v[48:51], v[148:151], v[216:219], v[48:51]
	v_mfma_f32_16x16x32_bf16 v[52:55], v[156:159], v[216:219], v[52:55]
	v_mfma_f32_16x16x32_bf16 v[32:35], v[148:151], v[224:227], v[32:35]
	v_mfma_f32_16x16x32_bf16 v[36:39], v[156:159], v[224:227], v[36:39]
	v_mfma_f32_16x16x32_bf16 v[16:19], v[148:151], v[232:235], v[16:19]
	v_mfma_f32_16x16x32_bf16 v[20:23], v[156:159], v[232:235], v[20:23]
	v_mfma_f32_16x16x32_bf16 v[0:3], v[148:151], v[240:243], v[0:3]
	v_mfma_f32_16x16x32_bf16 v[4:7], v[156:159], v[240:243], v[4:7]
	s_barrier
	s_add_i32 s85, s85, 2
	s_add_u32 s6, s6, 0x100
	s_addc_u32 s7, s7, 0
	s_add_u32 s82, s82, 0x100
	s_addc_u32 s83, s83, 0
	s_cmp_gt_u32 s85, 13
	s_cbranch_scc0 .LBB0_241
	s_and_b64 vcc, exec, s[46:47]
	s_cbranch_vccz .LBB0_244
	s_barrier

; #define PG8_STAGE(bufoff, gbase, voff) do { _Pragma("unroll") for (int _i = 0; _i < 2; ++_i) \
;         __builtin_amdgcn_global_load_lds((const unsigned*)((const char*)(gbase) + (voff)[_i]), (PG8_LAS unsigned*)(lds + (bufoff) + ldsw + _i * 8192), 16, 0, 0); } while (0)
; #define PG8_LDA(dst, b, h) do { _Pragma("unroll") for (int m = 0; m < 4; ++m) _Pragma("unroll") for (int k = 0; k < 2; ++k) dst[m][k] = *(const PG8_LAS bf16x8*)(lds + PG8_SA(b, h) + aoff + m * 2048 + k * 1024); } while (0)
; #define PG8_LDB(dst, b, h) do { _Pragma("unroll") for (int n = 0; n < 2; ++n) _Pragma("unroll") for (int k = 0; k < 2; ++k) dst[n][k] = *(const PG8_LAS bf16x8*)(lds + PG8_SB(b, h) + boff + n * 2048 + k * 1024); } while (0)
; #define PG8_MMA(ai, bj, At, Bt) do { __builtin_amdgcn_s_setprio(1); _Pragma("unroll") for (int m = 0; m < 4; ++m) _Pragma("unroll") for (int n = 0; n < 2; ++n) _Pragma("unroll") for (int k = 0; k < 2; ++k) \
;         acc[ai][bj][m][n] = __builtin_amdgcn_mfma_f32_16x16x32_bf16(Bt[n][k], At[m][k], acc[ai][bj][m][n], 0, 0, 0); __builtin_amdgcn_s_setprio(0); } while (0)
; #define PG8_WAIT_V(n) asm volatile("s_waitcnt vmcnt(" #n ")" ::: "memory")
; #define PG8_BAR __builtin_amdgcn_s_barrier()
; template <class Epi, class Sched, bool ALIGN_EPI = false, bool SP2 = false>
; __device__ __forceinline__ void gemm_phase(PG8_LAS unsigned char* lds, const Gemm g, const Sched& S, const Epi& E) {
;     ...
;         for (int t = 0; t < nt; t += 2) {
;             const bool last = (t == nt - 2);
;             const char* a1 = cA + (size_t)(t + 1) * kstep;
;             const char* a2 = last ? nA : cA + (size_t)(t + 2) * kstep; const char* b2 = last ? nB : cB + (size_t)(t + 2) * kstep;
;             const char* a3 = a2 + kstep; const char* b3 = b2 + kstep;
;             if (last && has_next) S.a_ready(nxt);
;             if constexpr (SP2) {
;             PG8_LDB(B0, 0, 0); PG8_LDB(B1, 0, 1); PG8_SCHED; PG8_LDA(At, 0, 0); PG8_STAGE(PG8_SA(1, 1), a1 + hstep, voffA);
;             PG8_WAIT_V(8); PG8_WAIT_L(0); PG8_BAR; PG8_MMA(0, 0, At, B0); PG8_MMA(0, 1, At, B1); PG8_BAR; PG8_SCHED;
;             PG8_LDA(At, 0, 1); PG8_STAGE(PG8_SB(0, 0), b2, voffB); PG8_STAGE(PG8_SB(0, 1), b2 + hstep, voffB); PG8_STAGE(PG8_SA(0, 0), a2, voffA);
;             PG8_WAIT_V(8); PG8_WAIT_L(0); PG8_BAR; PG8_MMA(1, 0, At, B0); PG8_MMA(1, 1, At, B1); PG8_BAR; PG8_SCHED;
.LBB0_513:
	ds_read_b128 v[144:147], v153
	ds_read_b128 v[156:159], v153 offset:1024
	ds_read_b128 v[160:163], v153 offset:2048
	ds_read_b128 v[164:167], v153 offset:3072
	ds_read_b128 v[168:171], v154
	ds_read_b128 v[172:175], v154 offset:1024
	ds_read_b128 v[176:179], v154 offset:2048
	ds_read_b128 v[182:185], v154 offset:3072
	s_add_u32 s30, s28, 0xfffc0080
	s_addc_u32 s31, s29, -1
	s_cmp_eq_u32 s53, 12
	s_cselect_b32 s37, s15, s31
	s_cselect_b32 s36, s49, s30
	s_cselect_b32 s31, s11, s52
	s_cselect_b32 s30, s50, s51
	v_lshl_add_u64 v[148:149], s[28:29], 0, v[136:137]
	s_add_i32 m0, s27, 0xc000
	ds_read_b128 v[186:189], v155
	ds_read_b128 v[194:197], v155 offset:1024
	ds_read_b128 v[198:201], v155 offset:2048
	ds_read_b128 v[202:205], v155 offset:3072
	ds_read_b128 v[206:209], v155 offset:4096
	ds_read_b128 v[210:213], v155 offset:5120
	ds_read_b128 v[214:217], v155 offset:6144
	ds_read_b128 v[218:221], v155 offset:7168
	global_load_lds_dwordx4 v[148:149], off
	v_lshl_add_u64 v[148:149], s[28:29], 0, v[138:139]
	s_add_i32 m0, s27, 0xe000
	s_nop 0
	global_load_lds_dwordx4 v[148:149], off
	s_waitcnt vmcnt(8)
	s_waitcnt lgkmcnt(0)
	s_barrier
	s_waitcnt lgkmcnt(0)
	v_mfma_f32_16x16x32_bf16 v[124:127], v[144:147], v[186:189], v[124:127]
	v_mfma_f32_16x16x32_bf16 v[120:123], v[160:163], v[186:189], v[120:123]
	v_mfma_f32_16x16x32_bf16 v[108:111], v[144:147], v[198:201], v[108:111]
	v_mfma_f32_16x16x32_bf16 v[104:107], v[160:163], v[198:201], v[104:107]
	v_mfma_f32_16x16x32_bf16 v[92:95], v[144:147], v[206:209], v[92:95]
	v_mfma_f32_16x16x32_bf16 v[88:91], v[160:163], v[206:209], v[88:91]
	v_mfma_f32_16x16x32_bf16 v[76:79], v[144:147], v[214:217], v[76:79]
	v_mfma_f32_16x16x32_bf16 v[72:75], v[160:163], v[214:217], v[72:75]
	v_mfma_f32_16x16x32_bf16 v[124:127], v[156:159], v[194:197], v[124:127]
	v_mfma_f32_16x16x32_bf16 v[120:123], v[164:167], v[194:197], v[120:123]
	v_mfma_f32_16x16x32_bf16 v[108:111], v[156:159], v[202:205], v[108:111]
	v_mfma_f32_16x16x32_bf16 v[104:107], v[164:167], v[202:205], v[104:107]
	v_mfma_f32_16x16x32_bf16 v[92:95], v[156:159], v[210:213], v[92:95]
	v_mfma_f32_16x16x32_bf16 v[88:91], v[164:167], v[210:213], v[88:91]
	v_mfma_f32_16x16x32_bf16 v[76:79], v[156:159], v[218:221], v[76:79]
	v_mfma_f32_16x16x32_bf16 v[72:75], v[164:167], v[218:221], v[72:75]
	v_mfma_f32_16x16x32_bf16 v[116:119], v[168:171], v[186:189], v[116:119]
	v_mfma_f32_16x16x32_bf16 v[112:115], v[176:179], v[186:189], v[112:115]
	v_mfma_f32_16x16x32_bf16 v[100:103], v[168:171], v[198:201], v[100:103]
	v_mfma_f32_16x16x32_bf16 v[96:99], v[176:179], v[198:201], v[96:99]
	v_mfma_f32_16x16x32_bf16 v[84:87], v[168:171], v[206:209], v[84:87]
	v_mfma_f32_16x16x32_bf16 v[80:83], v[176:179], v[206:209], v[80:83]
	v_mfma_f32_16x16x32_bf16 v[68:71], v[168:171], v[214:217], v[68:71]
	v_mfma_f32_16x16x32_bf16 v[64:67], v[176:179], v[214:217], v[64:67]
	v_mfma_f32_16x16x32_bf16 v[116:119], v[172:175], v[194:197], v[116:119]
	v_mfma_f32_16x16x32_bf16 v[112:115], v[182:185], v[194:197], v[112:115]
	v_mfma_f32_16x16x32_bf16 v[100:103], v[172:175], v[202:205], v[100:103]
	v_mfma_f32_16x16x32_bf16 v[96:99], v[182:185], v[202:205], v[96:99]
	v_mfma_f32_16x16x32_bf16 v[84:87], v[172:175], v[210:213], v[84:87]
	v_mfma_f32_16x16x32_bf16 v[80:83], v[182:185], v[210:213], v[80:83]
	v_mfma_f32_16x16x32_bf16 v[68:71], v[172:175], v[218:221], v[68:71]
	v_mfma_f32_16x16x32_bf16 v[64:67], v[182:185], v[218:221], v[64:67]
	s_barrier
	s_add_i32 s62, s46, s3
	v_lshl_add_u64 v[148:149], s[30:31], 0, v[132:133]
	s_mov_b32 m0, s62
	ds_read_b128 v[186:189], v155 offset:16384
	ds_read_b128 v[194:197], v155 offset:17408
	ds_read_b128 v[198:201], v155 offset:18432
	ds_read_b128 v[202:205], v155 offset:19456
	ds_read_b128 v[206:209], v155 offset:20480
	ds_read_b128 v[210:213], v155 offset:21504
	ds_read_b128 v[214:217], v155 offset:22528
	ds_read_b128 v[218:221], v155 offset:23552
	global_load_lds_dwordx4 v[148:149], off
	s_add_i32 m0, s62, 0x2000
	s_add_u32 s62, s30, 0x40000
	v_lshl_add_u64 v[190:191], s[30:31], 0, v[128:129]
	s_addc_u32 s63, s31, 0
	s_add_i32 s66, s47, s3
	global_load_lds_dwordx4 v[190:191], off
	v_lshl_add_u64 v[222:223], s[62:63], 0, v[132:133]
	s_mov_b32 m0, s66
	v_lshl_add_u64 v[224:225], s[36:37], 0, v[130:131]
	global_load_lds_dwordx4 v[222:223], off
	v_lshl_add_u64 v[222:223], s[62:63], 0, v[128:129]
	s_add_i32 m0, s66, 0x2000
	s_nop 0
	global_load_lds_dwordx4 v[222:223], off
	v_lshl_add_u64 v[222:223], s[36:37], 0, v[134:135]
	s_mov_b32 m0, s27
	s_nop 0
	global_load_lds_dwordx4 v[222:223], off
	s_mov_b32 m0, s33
	s_nop 0
	global_load_lds_dwordx4 v[224:225], off
	s_waitcnt vmcnt(8)
	s_waitcnt lgkmcnt(0)
	s_barrier
; #define PG8_STAGE(bufoff, gbase, voff) do { _Pragma("unroll") for (int _i = 0; _i < 2; ++_i) \
;         __builtin_amdgcn_global_load_lds((const unsigned*)((const char*)(gbase) + (voff)[_i]), (PG8_LAS unsigned*)(lds + (bufoff) + ldsw + _i * 8192), 16, 0, 0); } while (0)
; #define PG8_LDA(dst, b, h) do { _Pragma("unroll") for (int m = 0; m < 4; ++m) _Pragma("unroll") for (int k = 0; k < 2; ++k) dst[m][k] = *(const PG8_LAS bf16x8*)(lds + PG8_SA(b, h) + aoff + m * 2048 + k * 1024); } while (0)
; #define PG8_LDB(dst, b, h) do { _Pragma("unroll") for (int n = 0; n < 2; ++n) _Pragma("unroll") for (int k = 0; k < 2; ++k) dst[n][k] = *(const PG8_LAS bf16x8*)(lds + PG8_SB(b, h) + boff + n * 2048 + k * 1024); } while (0)
; #define PG8_MMA(ai, bj, At, Bt) do { __builtin_amdgcn_s_setprio(1); _Pragma("unroll") for (int m = 0; m < 4; ++m) _Pragma("unroll") for (int n = 0; n < 2; ++n) _Pragma("unroll") for (int k = 0; k < 2; ++k) \
;         acc[ai][bj][m][n] = __builtin_amdgcn_mfma_f32_16x16x32_bf16(Bt[n][k], At[m][k], acc[ai][bj][m][n], 0, 0, 0); __builtin_amdgcn_s_setprio(0); } while (0)
; #define PG8_WAIT_V(n) asm volatile("s_waitcnt vmcnt(" #n ")" ::: "memory")
; #define PG8_WAIT_L(n) asm volatile("s_waitcnt lgkmcnt(" #n ")" ::: "memory")
; #define PG8_BAR __builtin_amdgcn_s_barrier()
; #define PG8_SCHED __builtin_amdgcn_sched_barrier(0)
; template <class Epi, class Sched, bool ALIGN_EPI = false, bool SP2 = false>
; __device__ __forceinline__ void gemm_phase(PG8_LAS unsigned char* lds, const Gemm g, const Sched& S, const Epi& E) {
;     ...
;             PG8_WAIT_V(8); PG8_WAIT_L(0); PG8_BAR; PG8_MMA(1, 0, At, B0); PG8_MMA(1, 1, At, B1); PG8_BAR; PG8_SCHED;
;             PG8_LDB(B0, 1, 0); PG8_LDB(B1, 1, 1); PG8_SCHED; PG8_LDA(At, 1, 0); PG8_STAGE(PG8_SA(0, 1), a2 + hstep, voffA);
;             PG8_WAIT_V(8); PG8_WAIT_L(0); PG8_BAR; PG8_MMA(0, 0, At, B0); PG8_MMA(0, 1, At, B1); PG8_BAR; PG8_SCHED;
;             PG8_LDA(At, 1, 1); PG8_STAGE(PG8_SB(1, 0), b3, voffB); PG8_STAGE(PG8_SB(1, 1), b3 + hstep, voffB); PG8_STAGE(PG8_SA(1, 0), a3, voffA);
	s_waitcnt lgkmcnt(0)
	v_mfma_f32_16x16x32_bf16 v[60:63], v[144:147], v[186:189], v[60:63]
	v_mfma_f32_16x16x32_bf16 v[56:59], v[160:163], v[186:189], v[56:59]
	v_mfma_f32_16x16x32_bf16 v[44:47], v[144:147], v[198:201], v[44:47]
	v_mfma_f32_16x16x32_bf16 v[40:43], v[160:163], v[198:201], v[40:43]
	v_mfma_f32_16x16x32_bf16 v[28:31], v[144:147], v[206:209], v[28:31]
	v_mfma_f32_16x16x32_bf16 v[24:27], v[160:163], v[206:209], v[24:27]
	v_mfma_f32_16x16x32_bf16 v[12:15], v[144:147], v[214:217], v[12:15]
	v_mfma_f32_16x16x32_bf16 v[8:11], v[160:163], v[214:217], v[8:11]
	v_mfma_f32_16x16x32_bf16 v[60:63], v[156:159], v[194:197], v[60:63]
	v_mfma_f32_16x16x32_bf16 v[56:59], v[164:167], v[194:197], v[56:59]
	v_mfma_f32_16x16x32_bf16 v[44:47], v[156:159], v[202:205], v[44:47]
	v_mfma_f32_16x16x32_bf16 v[40:43], v[164:167], v[202:205], v[40:43]
	v_mfma_f32_16x16x32_bf16 v[28:31], v[156:159], v[210:213], v[28:31]
	v_mfma_f32_16x16x32_bf16 v[24:27], v[164:167], v[210:213], v[24:27]
	v_mfma_f32_16x16x32_bf16 v[12:15], v[156:159], v[218:221], v[12:15]
	v_mfma_f32_16x16x32_bf16 v[8:11], v[164:167], v[218:221], v[8:11]
	v_mfma_f32_16x16x32_bf16 v[52:55], v[168:171], v[186:189], v[52:55]
	v_mfma_f32_16x16x32_bf16 v[48:51], v[176:179], v[186:189], v[48:51]
	v_mfma_f32_16x16x32_bf16 v[36:39], v[168:171], v[198:201], v[36:39]
	v_mfma_f32_16x16x32_bf16 v[32:35], v[176:179], v[198:201], v[32:35]
	v_mfma_f32_16x16x32_bf16 v[20:23], v[168:171], v[206:209], v[20:23]
	v_mfma_f32_16x16x32_bf16 v[16:19], v[176:179], v[206:209], v[16:19]
	v_mfma_f32_16x16x32_bf16 v[4:7], v[168:171], v[214:217], v[4:7]
	v_mfma_f32_16x16x32_bf16 v[0:3], v[176:179], v[214:217], v[0:3]
	v_mfma_f32_16x16x32_bf16 v[52:55], v[172:175], v[194:197], v[52:55]
	v_mfma_f32_16x16x32_bf16 v[48:51], v[182:185], v[194:197], v[48:51]
	v_mfma_f32_16x16x32_bf16 v[36:39], v[172:175], v[202:205], v[36:39]
	v_mfma_f32_16x16x32_bf16 v[32:35], v[182:185], v[202:205], v[32:35]
	v_mfma_f32_16x16x32_bf16 v[20:23], v[172:175], v[210:213], v[20:23]
	v_mfma_f32_16x16x32_bf16 v[16:19], v[182:185], v[210:213], v[16:19]
	v_mfma_f32_16x16x32_bf16 v[4:7], v[172:175], v[218:221], v[4:7]
	v_mfma_f32_16x16x32_bf16 v[0:3], v[182:185], v[218:221], v[0:3]
	s_barrier
	s_add_i32 s62, 0, 0x18000
	s_add_i32 s63, 0, 0x1c000
	v_add_u32_e32 v164, s62, v151
	v_add_u32_e32 v181, s63, v151
	ds_read_b128 v[144:147], v164
	ds_read_b128 v[156:159], v164 offset:1024
	ds_read_b128 v[160:163], v164 offset:2048
	ds_read_b128 v[164:167], v164 offset:3072
	ds_read_b128 v[168:171], v181
	ds_read_b128 v[172:175], v181 offset:1024
	ds_read_b128 v[176:179], v181 offset:2048
	ds_read_b128 v[182:185], v181 offset:3072
	s_add_u32 s36, s36, 0x40000
	s_addc_u32 s37, s37, 0
	s_mov_b32 m0, s38
	v_lshl_add_u64 v[226:227], s[36:37], 0, v[134:135]
	ds_read_b128 v[186:189], v155 offset:32768
	ds_read_b128 v[194:197], v155 offset:33792
	ds_read_b128 v[198:201], v155 offset:34816
	ds_read_b128 v[202:205], v155 offset:35840
	ds_read_b128 v[206:209], v155 offset:36864
	ds_read_b128 v[210:213], v155 offset:37888
	ds_read_b128 v[214:217], v155 offset:38912
	ds_read_b128 v[218:221], v155 offset:39936
	global_load_lds_dwordx4 v[226:227], off
	v_lshl_add_u64 v[226:227], s[36:37], 0, v[130:131]
	s_mov_b32 m0, s39
	s_nop 0
	global_load_lds_dwordx4 v[226:227], off
	s_waitcnt vmcnt(8)
	s_waitcnt lgkmcnt(0)
	s_barrier
	s_waitcnt lgkmcnt(0)
	v_mfma_f32_16x16x32_bf16 v[124:127], v[144:147], v[186:189], v[124:127]
	v_mfma_f32_16x16x32_bf16 v[120:123], v[160:163], v[186:189], v[120:123]
	v_mfma_f32_16x16x32_bf16 v[108:111], v[144:147], v[198:201], v[108:111]
	v_mfma_f32_16x16x32_bf16 v[104:107], v[160:163], v[198:201], v[104:107]
	v_mfma_f32_16x16x32_bf16 v[92:95], v[144:147], v[206:209], v[92:95]
	v_mfma_f32_16x16x32_bf16 v[88:91], v[160:163], v[206:209], v[88:91]
	v_mfma_f32_16x16x32_bf16 v[76:79], v[144:147], v[214:217], v[76:79]
	v_mfma_f32_16x16x32_bf16 v[72:75], v[160:163], v[214:217], v[72:75]
	v_mfma_f32_16x16x32_bf16 v[124:127], v[156:159], v[194:197], v[124:127]
	v_mfma_f32_16x16x32_bf16 v[120:123], v[164:167], v[194:197], v[120:123]
	v_mfma_f32_16x16x32_bf16 v[108:111], v[156:159], v[202:205], v[108:111]
	v_mfma_f32_16x16x32_bf16 v[104:107], v[164:167], v[202:205], v[104:107]
	v_mfma_f32_16x16x32_bf16 v[92:95], v[156:159], v[210:213], v[92:95]
	v_mfma_f32_16x16x32_bf16 v[88:91], v[164:167], v[210:213], v[88:91]
	v_mfma_f32_16x16x32_bf16 v[76:79], v[156:159], v[218:221], v[76:79]
	v_mfma_f32_16x16x32_bf16 v[72:75], v[164:167], v[218:221], v[72:75]
	v_mfma_f32_16x16x32_bf16 v[116:119], v[168:171], v[186:189], v[116:119]
	v_mfma_f32_16x16x32_bf16 v[112:115], v[176:179], v[186:189], v[112:115]
	v_mfma_f32_16x16x32_bf16 v[100:103], v[168:171], v[198:201], v[100:103]
	v_mfma_f32_16x16x32_bf16 v[96:99], v[176:179], v[198:201], v[96:99]
	v_mfma_f32_16x16x32_bf16 v[84:87], v[168:171], v[206:209], v[84:87]
	v_mfma_f32_16x16x32_bf16 v[80:83], v[176:179], v[206:209], v[80:83]
	v_mfma_f32_16x16x32_bf16 v[68:71], v[168:171], v[214:217], v[68:71]
	v_mfma_f32_16x16x32_bf16 v[64:67], v[176:179], v[214:217], v[64:67]
	v_mfma_f32_16x16x32_bf16 v[116:119], v[172:175], v[194:197], v[116:119]
	v_mfma_f32_16x16x32_bf16 v[112:115], v[182:185], v[194:197], v[112:115]
	v_mfma_f32_16x16x32_bf16 v[100:103], v[172:175], v[202:205], v[100:103]
	v_mfma_f32_16x16x32_bf16 v[96:99], v[182:185], v[202:205], v[96:99]
	v_mfma_f32_16x16x32_bf16 v[84:87], v[172:175], v[210:213], v[84:87]
	v_mfma_f32_16x16x32_bf16 v[80:83], v[182:185], v[210:213], v[80:83]
	v_mfma_f32_16x16x32_bf16 v[68:71], v[172:175], v[218:221], v[68:71]
	v_mfma_f32_16x16x32_bf16 v[64:67], v[182:185], v[218:221], v[64:67]
	s_barrier
; #define PG8_STAGE(bufoff, gbase, voff) do { _Pragma("unroll") for (int _i = 0; _i < 2; ++_i) \
;         __builtin_amdgcn_global_load_lds((const unsigned*)((const char*)(gbase) + (voff)[_i]), (PG8_LAS unsigned*)(lds + (bufoff) + ldsw + _i * 8192), 16, 0, 0); } while (0)
; #define PG8_LDA(dst, b, h) do { _Pragma("unroll") for (int m = 0; m < 4; ++m) _Pragma("unroll") for (int k = 0; k < 2; ++k) dst[m][k] = *(const PG8_LAS bf16x8*)(lds + PG8_SA(b, h) + aoff + m * 2048 + k * 1024); } while (0)
; #define PG8_WAIT_V(n) asm volatile("s_waitcnt vmcnt(" #n ")" ::: "memory")
; template <class Epi, class Sched, bool ALIGN_EPI = false, bool SP2 = false>
; __device__ __forceinline__ void gemm_phase(PG8_LAS unsigned char* lds, const Gemm g, const Sched& S, const Epi& E) {
;     ...
;             PG8_LDA(At, 1, 1); PG8_STAGE(PG8_SB(1, 0), b3, voffB); PG8_STAGE(PG8_SB(1, 1), b3 + hstep, voffB); PG8_STAGE(PG8_SA(1, 0), a3, voffA);
;             PG8_WAIT_V(8); PG8_WAIT_L(0); PG8_BAR; PG8_MMA(1, 0, At, B0); PG8_MMA(1, 1, At, B1); PG8_BAR; PG8_SCHED;
;             } else {
;             PG8_LDB(B0, 0, 0); PG8_SCHED; PG8_LDA(At, 0, 0); PG8_STAGE(PG8_SA(1, 1), a1 + hstep, voffA);
;             PG8_WAIT_L(8); PG8_BAR; PG8_WAIT_L(0); PG8_MMA(0, 0, At, B0); PG8_BAR; PG8_SCHED;
;             PG8_LDB(B1, 0, 1); PG8_STAGE(PG8_SB(0, 0), b2, voffB);
;             PG8_BAR; PG8_WAIT_L(0); PG8_MMA(0, 1, At, B1); PG8_BAR;
;             PG8_LDA(At, 0, 1); PG8_STAGE(PG8_SA(0, 0), a2, voffA);
;             PG8_BAR; PG8_WAIT_L(0); PG8_MMA(1, 0, At, B0); PG8_BAR; PG8_SCHED;
;             PG8_STAGE(PG8_SB(0, 1), b2 + hstep, voffB);
;             PG8_WAIT_V(6); PG8_BAR; PG8_MMA(1, 1, At, B1); PG8_BAR;
;             PG8_LDB(B0, 1, 0); PG8_SCHED; PG8_LDA(At, 1, 0); PG8_STAGE(PG8_SA(0, 1), a2 + hstep, voffA);
;             PG8_WAIT_L(8); PG8_BAR; PG8_WAIT_L(0); PG8_MMA(0, 0, At, B0); PG8_BAR; PG8_SCHED;
;             PG8_LDB(B1, 1, 1); PG8_STAGE(PG8_SB(1, 0), b3, voffB);
;             PG8_BAR; PG8_WAIT_L(0); PG8_MMA(0, 1, At, B1); PG8_BAR;
;             PG8_LDA(At, 1, 1); PG8_STAGE(PG8_SA(1, 0), a3, voffA);
;             PG8_BAR; PG8_WAIT_L(0); PG8_MMA(1, 0, At, B0); PG8_BAR; PG8_SCHED;
;             PG8_STAGE(PG8_SB(1, 1), b3 + hstep, voffB);
;             PG8_WAIT_V(6); PG8_BAR; PG8_MMA(1, 1, At, B1); PG8_BAR;
;             }
;         }
;         if constexpr (ALIGN_EPI) { if (wr == 0) PG8_BAR; }
	s_add_i32 s36, s62, s3
	v_lshl_add_u64 v[148:149], v[148:149], 0, s[6:7]
	s_mov_b32 m0, s36
	ds_read_b128 v[186:189], v155 offset:49152
	ds_read_b128 v[194:197], v155 offset:50176
	ds_read_b128 v[198:201], v155 offset:51200
	ds_read_b128 v[202:205], v155 offset:52224
	ds_read_b128 v[206:209], v155 offset:53248
	ds_read_b128 v[210:213], v155 offset:54272
	ds_read_b128 v[214:217], v155 offset:55296
	ds_read_b128 v[218:221], v155 offset:56320
	global_load_lds_dwordx4 v[148:149], off
	s_add_i32 m0, s36, 0x2000
	s_add_u32 s30, s30, 0x40080
	v_lshl_add_u64 v[148:149], v[190:191], 0, s[6:7]
	s_addc_u32 s31, s31, 0
	s_add_i32 s36, s63, s3
	global_load_lds_dwordx4 v[148:149], off
	v_lshl_add_u64 v[148:149], s[30:31], 0, v[132:133]
	s_mov_b32 m0, s36
	s_nop 0
	global_load_lds_dwordx4 v[148:149], off
	v_lshl_add_u64 v[148:149], s[30:31], 0, v[128:129]
	s_add_i32 m0, s36, 0x2000
	s_nop 0
	global_load_lds_dwordx4 v[148:149], off
	v_lshl_add_u64 v[148:149], v[222:223], 0, s[6:7]
	s_mov_b32 m0, s42
	s_nop 0
	global_load_lds_dwordx4 v[148:149], off
	v_lshl_add_u64 v[148:149], v[224:225], 0, s[6:7]
	s_mov_b32 m0, s43
	s_nop 0
	global_load_lds_dwordx4 v[148:149], off
	s_waitcnt vmcnt(8)
	s_waitcnt lgkmcnt(0)
	s_barrier
	s_waitcnt lgkmcnt(0)
	v_mfma_f32_16x16x32_bf16 v[60:63], v[144:147], v[186:189], v[60:63]
	v_mfma_f32_16x16x32_bf16 v[56:59], v[160:163], v[186:189], v[56:59]
	v_mfma_f32_16x16x32_bf16 v[44:47], v[144:147], v[198:201], v[44:47]
	v_mfma_f32_16x16x32_bf16 v[40:43], v[160:163], v[198:201], v[40:43]
	v_mfma_f32_16x16x32_bf16 v[28:31], v[144:147], v[206:209], v[28:31]
	v_mfma_f32_16x16x32_bf16 v[24:27], v[160:163], v[206:209], v[24:27]
	v_mfma_f32_16x16x32_bf16 v[12:15], v[144:147], v[214:217], v[12:15]
	v_mfma_f32_16x16x32_bf16 v[8:11], v[160:163], v[214:217], v[8:11]
	v_mfma_f32_16x16x32_bf16 v[60:63], v[156:159], v[194:197], v[60:63]
	v_mfma_f32_16x16x32_bf16 v[56:59], v[164:167], v[194:197], v[56:59]
	v_mfma_f32_16x16x32_bf16 v[44:47], v[156:159], v[202:205], v[44:47]
	v_mfma_f32_16x16x32_bf16 v[40:43], v[164:167], v[202:205], v[40:43]
	v_mfma_f32_16x16x32_bf16 v[28:31], v[156:159], v[210:213], v[28:31]
	v_mfma_f32_16x16x32_bf16 v[24:27], v[164:167], v[210:213], v[24:27]
	v_mfma_f32_16x16x32_bf16 v[12:15], v[156:159], v[218:221], v[12:15]
	v_mfma_f32_16x16x32_bf16 v[8:11], v[164:167], v[218:221], v[8:11]
	v_mfma_f32_16x16x32_bf16 v[52:55], v[168:171], v[186:189], v[52:55]
	v_mfma_f32_16x16x32_bf16 v[48:51], v[176:179], v[186:189], v[48:51]
	v_mfma_f32_16x16x32_bf16 v[36:39], v[168:171], v[198:201], v[36:39]
	v_mfma_f32_16x16x32_bf16 v[32:35], v[176:179], v[198:201], v[32:35]
	v_mfma_f32_16x16x32_bf16 v[20:23], v[168:171], v[206:209], v[20:23]
	v_mfma_f32_16x16x32_bf16 v[16:19], v[176:179], v[206:209], v[16:19]
	v_mfma_f32_16x16x32_bf16 v[4:7], v[168:171], v[214:217], v[4:7]
	v_mfma_f32_16x16x32_bf16 v[0:3], v[176:179], v[214:217], v[0:3]
	v_mfma_f32_16x16x32_bf16 v[52:55], v[172:175], v[194:197], v[52:55]
	v_mfma_f32_16x16x32_bf16 v[48:51], v[182:185], v[194:197], v[48:51]
	v_mfma_f32_16x16x32_bf16 v[36:39], v[172:175], v[202:205], v[36:39]
	v_mfma_f32_16x16x32_bf16 v[32:35], v[182:185], v[202:205], v[32:35]
	v_mfma_f32_16x16x32_bf16 v[20:23], v[172:175], v[210:213], v[20:23]
	v_mfma_f32_16x16x32_bf16 v[16:19], v[182:185], v[210:213], v[16:19]
	v_mfma_f32_16x16x32_bf16 v[4:7], v[172:175], v[218:221], v[4:7]
	v_mfma_f32_16x16x32_bf16 v[0:3], v[182:185], v[218:221], v[0:3]
	s_barrier
	s_add_i32 s53, s53, 2
	s_add_u32 s28, s28, 0x100
	s_addc_u32 s29, s29, 0
	s_add_u32 s51, s51, 0x100
	s_addc_u32 s52, s52, 0
	s_cmp_gt_u32 s53, 13
	s_cbranch_scc0 .LBB0_513
	s_and_b64 vcc, exec, s[8:9]
	s_cbranch_vccz .LBB0_516
	s_barrier

; #define PG8_STAGE(bufoff, gbase, voff) do { _Pragma("unroll") for (int _i = 0; _i < 2; ++_i) \
;         __builtin_amdgcn_global_load_lds((const unsigned*)((const char*)(gbase) + (voff)[_i]), (PG8_LAS unsigned*)(lds + (bufoff) + ldsw + _i * 8192), 16, 0, 0); } while (0)
; #define PG8_LDA(dst, b, h) do { _Pragma("unroll") for (int m = 0; m < 4; ++m) _Pragma("unroll") for (int k = 0; k < 2; ++k) dst[m][k] = *(const PG8_LAS bf16x8*)(lds + PG8_SA(b, h) + aoff + m * 2048 + k * 1024); } while (0)
; #define PG8_LDB(dst, b, h) do { _Pragma("unroll") for (int n = 0; n < 2; ++n) _Pragma("unroll") for (int k = 0; k < 2; ++k) dst[n][k] = *(const PG8_LAS bf16x8*)(lds + PG8_SB(b, h) + boff + n * 2048 + k * 1024); } while (0)
; #define PG8_MMA(ai, bj, At, Bt) do { __builtin_amdgcn_s_setprio(1); _Pragma("unroll") for (int m = 0; m < 4; ++m) _Pragma("unroll") for (int n = 0; n < 2; ++n) _Pragma("unroll") for (int k = 0; k < 2; ++k) \
;         acc[ai][bj][m][n] = __builtin_amdgcn_mfma_f32_16x16x32_bf16(Bt[n][k], At[m][k], acc[ai][bj][m][n], 0, 0, 0); __builtin_amdgcn_s_setprio(0); } while (0)
; #define PG8_WAIT_V(n) asm volatile("s_waitcnt vmcnt(" #n ")" ::: "memory")
; #define PG8_BAR __builtin_amdgcn_s_barrier()
; template <class Epi, class Sched, bool ALIGN_EPI = false, bool SP2 = false>
; __device__ __forceinline__ void gemm_phase(PG8_LAS unsigned char* lds, const Gemm g, const Sched& S, const Epi& E) {
;     ...
;         for (int t = 0; t < nt; t += 2) {
;             const bool last = (t == nt - 2);
;             const char* a1 = cA + (size_t)(t + 1) * kstep;
;             const char* a2 = last ? nA : cA + (size_t)(t + 2) * kstep; const char* b2 = last ? nB : cB + (size_t)(t + 2) * kstep;
;             const char* a3 = a2 + kstep; const char* b3 = b2 + kstep;
;             if (last && has_next) S.a_ready(nxt);
;             if constexpr (SP2) {
;             PG8_LDB(B0, 0, 0); PG8_LDB(B1, 0, 1); PG8_SCHED; PG8_LDA(At, 0, 0); PG8_STAGE(PG8_SA(1, 1), a1 + hstep, voffA);
;             PG8_WAIT_V(8); PG8_WAIT_L(0); PG8_BAR; PG8_MMA(0, 0, At, B0); PG8_MMA(0, 1, At, B1); PG8_BAR; PG8_SCHED;
;             PG8_LDA(At, 0, 1); PG8_STAGE(PG8_SB(0, 0), b2, voffB); PG8_STAGE(PG8_SB(0, 1), b2 + hstep, voffB); PG8_STAGE(PG8_SA(0, 0), a2, voffA);
;             PG8_WAIT_V(8); PG8_WAIT_L(0); PG8_BAR; PG8_MMA(1, 0, At, B0); PG8_MMA(1, 1, At, B1); PG8_BAR; PG8_SCHED;
.LBB0_586:
	s_add_u32 s22, s48, s18
	s_addc_u32 s23, s49, s19
	s_add_u32 s22, s22, 0xb000100
	s_addc_u32 s23, s23, 0
	s_add_u32 s53, s50, s18
	s_addc_u32 s62, s51, s19
	s_add_i32 s63, 0, 0x10000
	s_cmpk_eq_i32 s18, 0x700
	s_cselect_b32 s25, s5, s23
	s_cselect_b32 s24, s4, s22
	v_add_u32_e32 v161, s63, v159
	s_cselect_b32 s23, s1, s62
	s_cselect_b32 s22, s0, s53
	s_add_i32 s53, 0, 0x14000
	ds_read_b128 v[162:165], v161
	ds_read_b128 v[166:169], v161 offset:1024
	ds_read_b128 v[170:173], v161 offset:2048
	ds_read_b128 v[174:177], v161 offset:3072
	v_add_u32_e32 v161, s53, v159
	ds_read_b128 v[182:185], v161
	ds_read_b128 v[186:189], v161 offset:1024
	ds_read_b128 v[194:197], v161 offset:2048
	ds_read_b128 v[198:201], v161 offset:3072
	v_lshl_add_u64 v[178:179], v[140:141], 0, s[18:19]
	s_add_i32 m0, s16, 0xc000
	ds_read_b128 v[202:205], v160
	ds_read_b128 v[206:209], v160 offset:1024
	ds_read_b128 v[210:213], v160 offset:2048
	ds_read_b128 v[214:217], v160 offset:3072
	ds_read_b128 v[218:221], v160 offset:4096
	ds_read_b128 v[222:225], v160 offset:5120
	ds_read_b128 v[226:229], v160 offset:6144
	ds_read_b128 v[230:233], v160 offset:7168
	global_load_lds_dwordx4 v[178:179], off
	v_lshl_add_u64 v[178:179], v[142:143], 0, s[18:19]
	s_add_i32 m0, s16, 0xe000
	s_nop 0
	global_load_lds_dwordx4 v[178:179], off
	s_waitcnt vmcnt(8)
	s_waitcnt lgkmcnt(0)
	s_barrier
	s_waitcnt lgkmcnt(0)
	v_mfma_f32_16x16x32_bf16 v[124:127], v[162:165], v[202:205], v[124:127]
	v_mfma_f32_16x16x32_bf16 v[120:123], v[170:173], v[202:205], v[120:123]
	v_mfma_f32_16x16x32_bf16 v[112:115], v[162:165], v[210:213], v[112:115]
	v_mfma_f32_16x16x32_bf16 v[108:111], v[170:173], v[210:213], v[108:111]
	v_mfma_f32_16x16x32_bf16 v[100:103], v[162:165], v[218:221], v[100:103]
	v_mfma_f32_16x16x32_bf16 v[92:95], v[170:173], v[218:221], v[92:95]
	v_mfma_f32_16x16x32_bf16 v[84:87], v[162:165], v[226:229], v[84:87]
	v_mfma_f32_16x16x32_bf16 v[76:79], v[170:173], v[226:229], v[76:79]
	v_mfma_f32_16x16x32_bf16 v[124:127], v[166:169], v[206:209], v[124:127]
	v_mfma_f32_16x16x32_bf16 v[120:123], v[174:177], v[206:209], v[120:123]
	v_mfma_f32_16x16x32_bf16 v[112:115], v[166:169], v[214:217], v[112:115]
	v_mfma_f32_16x16x32_bf16 v[108:111], v[174:177], v[214:217], v[108:111]
	v_mfma_f32_16x16x32_bf16 v[100:103], v[166:169], v[222:225], v[100:103]
	v_mfma_f32_16x16x32_bf16 v[92:95], v[174:177], v[222:225], v[92:95]
	v_mfma_f32_16x16x32_bf16 v[84:87], v[166:169], v[230:233], v[84:87]
	v_mfma_f32_16x16x32_bf16 v[76:79], v[174:177], v[230:233], v[76:79]
	v_mfma_f32_16x16x32_bf16 v[116:119], v[182:185], v[202:205], v[116:119]
	v_mfma_f32_16x16x32_bf16 v[104:107], v[194:197], v[202:205], v[104:107]
	v_mfma_f32_16x16x32_bf16 v[96:99], v[182:185], v[210:213], v[96:99]
	v_mfma_f32_16x16x32_bf16 v[88:91], v[194:197], v[210:213], v[88:91]
	v_mfma_f32_16x16x32_bf16 v[80:83], v[182:185], v[218:221], v[80:83]
	v_mfma_f32_16x16x32_bf16 v[72:75], v[194:197], v[218:221], v[72:75]
	v_mfma_f32_16x16x32_bf16 v[68:71], v[182:185], v[226:229], v[68:71]
	v_mfma_f32_16x16x32_bf16 v[64:67], v[194:197], v[226:229], v[64:67]
	v_mfma_f32_16x16x32_bf16 v[116:119], v[186:189], v[206:209], v[116:119]
	v_mfma_f32_16x16x32_bf16 v[104:107], v[198:201], v[206:209], v[104:107]
	v_mfma_f32_16x16x32_bf16 v[96:99], v[186:189], v[214:217], v[96:99]
	v_mfma_f32_16x16x32_bf16 v[88:91], v[198:201], v[214:217], v[88:91]
	v_mfma_f32_16x16x32_bf16 v[80:83], v[186:189], v[222:225], v[80:83]
	v_mfma_f32_16x16x32_bf16 v[72:75], v[198:201], v[222:225], v[72:75]
	v_mfma_f32_16x16x32_bf16 v[68:71], v[186:189], v[230:233], v[68:71]
	v_mfma_f32_16x16x32_bf16 v[64:67], v[198:201], v[230:233], v[64:67]
	s_barrier
	s_add_i32 s62, s63, s13
	v_lshl_add_u64 v[178:179], s[22:23], 0, v[128:129]
	s_mov_b32 m0, s62
	ds_read_b128 v[202:205], v160 offset:16384
	ds_read_b128 v[206:209], v160 offset:17408
	ds_read_b128 v[210:213], v160 offset:18432
	ds_read_b128 v[214:217], v160 offset:19456
	ds_read_b128 v[218:221], v160 offset:20480
	ds_read_b128 v[222:225], v160 offset:21504
	ds_read_b128 v[226:229], v160 offset:22528
	ds_read_b128 v[230:233], v160 offset:23552
	global_load_lds_dwordx4 v[178:179], off
	s_add_i32 m0, s62, 0x2000
	s_add_u32 s62, s22, 0x40000
	v_lshl_add_u64 v[190:191], s[22:23], 0, v[130:131]
	s_addc_u32 s63, s23, 0
	s_add_i32 s53, s53, s13
	global_load_lds_dwordx4 v[190:191], off
	v_lshl_add_u64 v[234:235], s[62:63], 0, v[128:129]
	s_mov_b32 m0, s53
	v_lshl_add_u64 v[236:237], s[24:25], 0, v[130:131]
	global_load_lds_dwordx4 v[234:235], off
	v_lshl_add_u64 v[234:235], s[62:63], 0, v[130:131]
	s_add_i32 m0, s53, 0x2000
	s_nop 0
	global_load_lds_dwordx4 v[234:235], off
	v_lshl_add_u64 v[234:235], s[24:25], 0, v[128:129]
	s_mov_b32 m0, s16
	s_nop 0
	global_load_lds_dwordx4 v[234:235], off
	s_mov_b32 m0, s43
	s_nop 0
	global_load_lds_dwordx4 v[236:237], off
	s_waitcnt vmcnt(8)
	s_waitcnt lgkmcnt(0)
	s_barrier
; #define PG8_STAGE(bufoff, gbase, voff) do { _Pragma("unroll") for (int _i = 0; _i < 2; ++_i) \
;         __builtin_amdgcn_global_load_lds((const unsigned*)((const char*)(gbase) + (voff)[_i]), (PG8_LAS unsigned*)(lds + (bufoff) + ldsw + _i * 8192), 16, 0, 0); } while (0)
; #define PG8_LDA(dst, b, h) do { _Pragma("unroll") for (int m = 0; m < 4; ++m) _Pragma("unroll") for (int k = 0; k < 2; ++k) dst[m][k] = *(const PG8_LAS bf16x8*)(lds + PG8_SA(b, h) + aoff + m * 2048 + k * 1024); } while (0)
; #define PG8_LDB(dst, b, h) do { _Pragma("unroll") for (int n = 0; n < 2; ++n) _Pragma("unroll") for (int k = 0; k < 2; ++k) dst[n][k] = *(const PG8_LAS bf16x8*)(lds + PG8_SB(b, h) + boff + n * 2048 + k * 1024); } while (0)
; #define PG8_MMA(ai, bj, At, Bt) do { __builtin_amdgcn_s_setprio(1); _Pragma("unroll") for (int m = 0; m < 4; ++m) _Pragma("unroll") for (int n = 0; n < 2; ++n) _Pragma("unroll") for (int k = 0; k < 2; ++k) \
;         acc[ai][bj][m][n] = __builtin_amdgcn_mfma_f32_16x16x32_bf16(Bt[n][k], At[m][k], acc[ai][bj][m][n], 0, 0, 0); __builtin_amdgcn_s_setprio(0); } while (0)
; #define PG8_WAIT_V(n) asm volatile("s_waitcnt vmcnt(" #n ")" ::: "memory")
; #define PG8_WAIT_L(n) asm volatile("s_waitcnt lgkmcnt(" #n ")" ::: "memory")
; #define PG8_BAR __builtin_amdgcn_s_barrier()
; #define PG8_SCHED __builtin_amdgcn_sched_barrier(0)
; template <class Epi, class Sched, bool ALIGN_EPI = false, bool SP2 = false>
; __device__ __forceinline__ void gemm_phase(PG8_LAS unsigned char* lds, const Gemm g, const Sched& S, const Epi& E) {
;     ...
;             PG8_WAIT_V(8); PG8_WAIT_L(0); PG8_BAR; PG8_MMA(1, 0, At, B0); PG8_MMA(1, 1, At, B1); PG8_BAR; PG8_SCHED;
;             PG8_LDB(B0, 1, 0); PG8_LDB(B1, 1, 1); PG8_SCHED; PG8_LDA(At, 1, 0); PG8_STAGE(PG8_SA(0, 1), a2 + hstep, voffA);
;             PG8_WAIT_V(8); PG8_WAIT_L(0); PG8_BAR; PG8_MMA(0, 0, At, B0); PG8_MMA(0, 1, At, B1); PG8_BAR; PG8_SCHED;
;             PG8_LDA(At, 1, 1); PG8_STAGE(PG8_SB(1, 0), b3, voffB); PG8_STAGE(PG8_SB(1, 1), b3 + hstep, voffB); PG8_STAGE(PG8_SA(1, 0), a3, voffA);
	s_waitcnt lgkmcnt(0)
	v_mfma_f32_16x16x32_bf16 v[60:63], v[162:165], v[202:205], v[60:63]
	v_mfma_f32_16x16x32_bf16 v[56:59], v[170:173], v[202:205], v[56:59]
	v_mfma_f32_16x16x32_bf16 v[52:55], v[162:165], v[210:213], v[52:55]
	v_mfma_f32_16x16x32_bf16 v[44:47], v[170:173], v[210:213], v[44:47]
	v_mfma_f32_16x16x32_bf16 v[36:39], v[162:165], v[218:221], v[36:39]
	v_mfma_f32_16x16x32_bf16 v[32:35], v[170:173], v[218:221], v[32:35]
	v_mfma_f32_16x16x32_bf16 v[20:23], v[162:165], v[226:229], v[20:23]
	v_mfma_f32_16x16x32_bf16 v[16:19], v[170:173], v[226:229], v[16:19]
	v_mfma_f32_16x16x32_bf16 v[60:63], v[166:169], v[206:209], v[60:63]
	v_mfma_f32_16x16x32_bf16 v[56:59], v[174:177], v[206:209], v[56:59]
	v_mfma_f32_16x16x32_bf16 v[52:55], v[166:169], v[214:217], v[52:55]
	v_mfma_f32_16x16x32_bf16 v[44:47], v[174:177], v[214:217], v[44:47]
	v_mfma_f32_16x16x32_bf16 v[36:39], v[166:169], v[222:225], v[36:39]
	v_mfma_f32_16x16x32_bf16 v[32:35], v[174:177], v[222:225], v[32:35]
	v_mfma_f32_16x16x32_bf16 v[20:23], v[166:169], v[230:233], v[20:23]
	v_mfma_f32_16x16x32_bf16 v[16:19], v[174:177], v[230:233], v[16:19]
	v_mfma_f32_16x16x32_bf16 v[48:51], v[182:185], v[202:205], v[48:51]
	v_mfma_f32_16x16x32_bf16 v[40:43], v[194:197], v[202:205], v[40:43]
	v_mfma_f32_16x16x32_bf16 v[28:31], v[182:185], v[210:213], v[28:31]
	v_mfma_f32_16x16x32_bf16 v[24:27], v[194:197], v[210:213], v[24:27]
	v_mfma_f32_16x16x32_bf16 v[12:15], v[182:185], v[218:221], v[12:15]
	v_mfma_f32_16x16x32_bf16 v[8:11], v[194:197], v[218:221], v[8:11]
	v_mfma_f32_16x16x32_bf16 v[4:7], v[182:185], v[226:229], v[4:7]
	v_mfma_f32_16x16x32_bf16 v[0:3], v[194:197], v[226:229], v[0:3]
	v_mfma_f32_16x16x32_bf16 v[48:51], v[186:189], v[206:209], v[48:51]
	v_mfma_f32_16x16x32_bf16 v[40:43], v[198:201], v[206:209], v[40:43]
	v_mfma_f32_16x16x32_bf16 v[28:31], v[186:189], v[214:217], v[28:31]
	v_mfma_f32_16x16x32_bf16 v[24:27], v[198:201], v[214:217], v[24:27]
	v_mfma_f32_16x16x32_bf16 v[12:15], v[186:189], v[222:225], v[12:15]
	v_mfma_f32_16x16x32_bf16 v[8:11], v[198:201], v[222:225], v[8:11]
	v_mfma_f32_16x16x32_bf16 v[4:7], v[186:189], v[230:233], v[4:7]
	v_mfma_f32_16x16x32_bf16 v[0:3], v[198:201], v[230:233], v[0:3]
	s_barrier
	s_add_i32 s53, 0, 0x18000
	v_add_u32_e32 v161, s53, v159
	s_add_i32 s62, 0, 0x1c000
	ds_read_b128 v[162:165], v161
	ds_read_b128 v[166:169], v161 offset:1024
	ds_read_b128 v[170:173], v161 offset:2048
	ds_read_b128 v[174:177], v161 offset:3072
	v_add_u32_e32 v161, s62, v159
	ds_read_b128 v[182:185], v161
	ds_read_b128 v[186:189], v161 offset:1024
	ds_read_b128 v[194:197], v161 offset:2048
	ds_read_b128 v[198:201], v161 offset:3072
	s_add_u32 s24, s24, 0x40000
	s_addc_u32 s25, s25, 0
	s_mov_b32 m0, s44
	v_lshl_add_u64 v[238:239], s[24:25], 0, v[128:129]
	ds_read_b128 v[202:205], v160 offset:32768
	ds_read_b128 v[206:209], v160 offset:33792
	ds_read_b128 v[210:213], v160 offset:34816
	ds_read_b128 v[214:217], v160 offset:35840
	ds_read_b128 v[218:221], v160 offset:36864
	ds_read_b128 v[222:225], v160 offset:37888
	ds_read_b128 v[226:229], v160 offset:38912
	ds_read_b128 v[230:233], v160 offset:39936
	global_load_lds_dwordx4 v[238:239], off
	v_lshl_add_u64 v[238:239], s[24:25], 0, v[130:131]
	s_mov_b32 m0, s45
	s_nop 0
	global_load_lds_dwordx4 v[238:239], off
	s_waitcnt vmcnt(8)
	s_waitcnt lgkmcnt(0)
	s_barrier
	s_waitcnt lgkmcnt(0)
	v_mfma_f32_16x16x32_bf16 v[124:127], v[162:165], v[202:205], v[124:127]
	v_mfma_f32_16x16x32_bf16 v[120:123], v[170:173], v[202:205], v[120:123]
	v_mfma_f32_16x16x32_bf16 v[112:115], v[162:165], v[210:213], v[112:115]
	v_mfma_f32_16x16x32_bf16 v[108:111], v[170:173], v[210:213], v[108:111]
	v_mfma_f32_16x16x32_bf16 v[100:103], v[162:165], v[218:221], v[100:103]
	v_mfma_f32_16x16x32_bf16 v[92:95], v[170:173], v[218:221], v[92:95]
	v_mfma_f32_16x16x32_bf16 v[84:87], v[162:165], v[226:229], v[84:87]
	v_mfma_f32_16x16x32_bf16 v[76:79], v[170:173], v[226:229], v[76:79]
	v_mfma_f32_16x16x32_bf16 v[124:127], v[166:169], v[206:209], v[124:127]
	v_mfma_f32_16x16x32_bf16 v[120:123], v[174:177], v[206:209], v[120:123]
	v_mfma_f32_16x16x32_bf16 v[112:115], v[166:169], v[214:217], v[112:115]
	v_mfma_f32_16x16x32_bf16 v[108:111], v[174:177], v[214:217], v[108:111]
	v_mfma_f32_16x16x32_bf16 v[100:103], v[166:169], v[222:225], v[100:103]
	v_mfma_f32_16x16x32_bf16 v[92:95], v[174:177], v[222:225], v[92:95]
	v_mfma_f32_16x16x32_bf16 v[84:87], v[166:169], v[230:233], v[84:87]
	v_mfma_f32_16x16x32_bf16 v[76:79], v[174:177], v[230:233], v[76:79]
	v_mfma_f32_16x16x32_bf16 v[116:119], v[182:185], v[202:205], v[116:119]
	v_mfma_f32_16x16x32_bf16 v[104:107], v[194:197], v[202:205], v[104:107]
	v_mfma_f32_16x16x32_bf16 v[96:99], v[182:185], v[210:213], v[96:99]
	v_mfma_f32_16x16x32_bf16 v[88:91], v[194:197], v[210:213], v[88:91]
	v_mfma_f32_16x16x32_bf16 v[80:83], v[182:185], v[218:221], v[80:83]
	v_mfma_f32_16x16x32_bf16 v[72:75], v[194:197], v[218:221], v[72:75]
	v_mfma_f32_16x16x32_bf16 v[68:71], v[182:185], v[226:229], v[68:71]
	v_mfma_f32_16x16x32_bf16 v[64:67], v[194:197], v[226:229], v[64:67]
	v_mfma_f32_16x16x32_bf16 v[116:119], v[186:189], v[206:209], v[116:119]
	v_mfma_f32_16x16x32_bf16 v[104:107], v[198:201], v[206:209], v[104:107]
	v_mfma_f32_16x16x32_bf16 v[96:99], v[186:189], v[214:217], v[96:99]
	v_mfma_f32_16x16x32_bf16 v[88:91], v[198:201], v[214:217], v[88:91]
	v_mfma_f32_16x16x32_bf16 v[80:83], v[186:189], v[222:225], v[80:83]
	v_mfma_f32_16x16x32_bf16 v[72:75], v[198:201], v[222:225], v[72:75]
	v_mfma_f32_16x16x32_bf16 v[68:71], v[186:189], v[230:233], v[68:71]
	v_mfma_f32_16x16x32_bf16 v[64:67], v[198:201], v[230:233], v[64:67]
	s_barrier
; template <class Epi, class Sched, bool ALIGN_EPI = false, bool SP2 = false>
; __device__ __forceinline__ void gemm_phase(PG8_LAS unsigned char* lds, const Gemm g, const Sched& S, const Epi& E) {
;     ...
;             PG8_LDA(At, 1, 1); PG8_STAGE(PG8_SB(1, 0), b3, voffB); PG8_STAGE(PG8_SB(1, 1), b3 + hstep, voffB); PG8_STAGE(PG8_SA(1, 0), a3, voffA);
;             PG8_WAIT_V(8); PG8_WAIT_L(0); PG8_BAR; PG8_MMA(1, 0, At, B0); PG8_MMA(1, 1, At, B1); PG8_BAR; PG8_SCHED;
;             } else {
;             PG8_LDB(B0, 0, 0); PG8_SCHED; PG8_LDA(At, 0, 0); PG8_STAGE(PG8_SA(1, 1), a1 + hstep, voffA);
;             PG8_WAIT_L(8); PG8_BAR; PG8_WAIT_L(0); PG8_MMA(0, 0, At, B0); PG8_BAR; PG8_SCHED;
;             PG8_LDB(B1, 0, 1); PG8_STAGE(PG8_SB(0, 0), b2, voffB);
;             PG8_BAR; PG8_WAIT_L(0); PG8_MMA(0, 1, At, B1); PG8_BAR;
;             PG8_LDA(At, 0, 1); PG8_STAGE(PG8_SA(0, 0), a2, voffA);
;             PG8_BAR; PG8_WAIT_L(0); PG8_MMA(1, 0, At, B0); PG8_BAR; PG8_SCHED;
;             PG8_STAGE(PG8_SB(0, 1), b2 + hstep, voffB);
;             PG8_WAIT_V(6); PG8_BAR; PG8_MMA(1, 1, At, B1); PG8_BAR;
;             PG8_LDB(B0, 1, 0); PG8_SCHED; PG8_LDA(At, 1, 0); PG8_STAGE(PG8_SA(0, 1), a2 + hstep, voffA);
;             PG8_WAIT_L(8); PG8_BAR; PG8_WAIT_L(0); PG8_MMA(0, 0, At, B0); PG8_BAR; PG8_SCHED;
;             PG8_LDB(B1, 1, 1); PG8_STAGE(PG8_SB(1, 0), b3, voffB);
;             PG8_BAR; PG8_WAIT_L(0); PG8_MMA(0, 1, At, B1); PG8_BAR;
;             PG8_LDA(At, 1, 1); PG8_STAGE(PG8_SA(1, 0), a3, voffA);
;             PG8_BAR; PG8_WAIT_L(0); PG8_MMA(1, 0, At, B0); PG8_BAR; PG8_SCHED;
;             PG8_STAGE(PG8_SB(1, 1), b3 + hstep, voffB);
;             PG8_WAIT_V(6); PG8_BAR; PG8_MMA(1, 1, At, B1); PG8_BAR;
;             }
;         }
;         if constexpr (ALIGN_EPI) { if (wr == 0) PG8_BAR; }
;         if constexpr (!Epi::AFTER_DRAIN) { E(acc, cur, wr, wc, fr, fq); S.done(cur); }
;         if (!has_next) break;
; #pragma unroll
;         for (int a = 0; a < 2; ++a)
; #pragma unroll
;             for (int b = 0; b < 2; ++b)
; #pragma unroll
;                 for (int m = 0; m < 4; ++m)
; #pragma unroll
;                     for (int n = 0; n < 2; ++n) acc[a][b][m][n] = (f32x4){0.f, 0.f, 0.f, 0.f};
;         cur = nxt; cA = nA; cB = nB; ++ui;
;         if constexpr (ALIGN_EPI) { if (wr == 1) PG8_BAR; }
;     }
;     PG8_WAIT_V(0);
	s_add_i32 s24, s53, s13
	v_lshl_add_u64 v[178:179], v[178:179], 0, s[14:15]
	s_mov_b32 m0, s24
	ds_read_b128 v[202:205], v160 offset:49152
	ds_read_b128 v[206:209], v160 offset:50176
	ds_read_b128 v[210:213], v160 offset:51200
	ds_read_b128 v[214:217], v160 offset:52224
	ds_read_b128 v[218:221], v160 offset:53248
	ds_read_b128 v[222:225], v160 offset:54272
	ds_read_b128 v[226:229], v160 offset:55296
	ds_read_b128 v[230:233], v160 offset:56320
	global_load_lds_dwordx4 v[178:179], off
	s_add_i32 m0, s24, 0x2000
	s_add_u32 s22, s22, 0x40080
	v_lshl_add_u64 v[178:179], v[190:191], 0, s[14:15]
	s_addc_u32 s23, s23, 0
	s_add_i32 s24, s62, s13
	global_load_lds_dwordx4 v[178:179], off
	v_lshl_add_u64 v[178:179], s[22:23], 0, v[128:129]
	s_mov_b32 m0, s24
	s_nop 0
	global_load_lds_dwordx4 v[178:179], off
	v_lshl_add_u64 v[178:179], s[22:23], 0, v[130:131]
	s_add_i32 m0, s24, 0x2000
	s_nop 0
	global_load_lds_dwordx4 v[178:179], off
	v_lshl_add_u64 v[178:179], v[234:235], 0, s[14:15]
	s_mov_b32 m0, s46
	s_nop 0
	global_load_lds_dwordx4 v[178:179], off
	v_lshl_add_u64 v[178:179], v[236:237], 0, s[14:15]
	s_mov_b32 m0, s47
	s_nop 0
	global_load_lds_dwordx4 v[178:179], off
	s_waitcnt vmcnt(8)
	s_waitcnt lgkmcnt(0)
	s_barrier
	s_waitcnt lgkmcnt(0)
	v_mfma_f32_16x16x32_bf16 v[60:63], v[162:165], v[202:205], v[60:63]
	v_mfma_f32_16x16x32_bf16 v[56:59], v[170:173], v[202:205], v[56:59]
	v_mfma_f32_16x16x32_bf16 v[52:55], v[162:165], v[210:213], v[52:55]
	v_mfma_f32_16x16x32_bf16 v[44:47], v[170:173], v[210:213], v[44:47]
	v_mfma_f32_16x16x32_bf16 v[36:39], v[162:165], v[218:221], v[36:39]
	v_mfma_f32_16x16x32_bf16 v[32:35], v[170:173], v[218:221], v[32:35]
	v_mfma_f32_16x16x32_bf16 v[20:23], v[162:165], v[226:229], v[20:23]
	v_mfma_f32_16x16x32_bf16 v[16:19], v[170:173], v[226:229], v[16:19]
	v_mfma_f32_16x16x32_bf16 v[60:63], v[166:169], v[206:209], v[60:63]
	v_mfma_f32_16x16x32_bf16 v[56:59], v[174:177], v[206:209], v[56:59]
	v_mfma_f32_16x16x32_bf16 v[52:55], v[166:169], v[214:217], v[52:55]
	v_mfma_f32_16x16x32_bf16 v[44:47], v[174:177], v[214:217], v[44:47]
	v_mfma_f32_16x16x32_bf16 v[36:39], v[166:169], v[222:225], v[36:39]
	v_mfma_f32_16x16x32_bf16 v[32:35], v[174:177], v[222:225], v[32:35]
	v_mfma_f32_16x16x32_bf16 v[20:23], v[166:169], v[230:233], v[20:23]
	v_mfma_f32_16x16x32_bf16 v[16:19], v[174:177], v[230:233], v[16:19]
	v_mfma_f32_16x16x32_bf16 v[48:51], v[182:185], v[202:205], v[48:51]
	v_mfma_f32_16x16x32_bf16 v[40:43], v[194:197], v[202:205], v[40:43]
	v_mfma_f32_16x16x32_bf16 v[28:31], v[182:185], v[210:213], v[28:31]
	v_mfma_f32_16x16x32_bf16 v[24:27], v[194:197], v[210:213], v[24:27]
	v_mfma_f32_16x16x32_bf16 v[12:15], v[182:185], v[218:221], v[12:15]
	v_mfma_f32_16x16x32_bf16 v[8:11], v[194:197], v[218:221], v[8:11]
	v_mfma_f32_16x16x32_bf16 v[4:7], v[182:185], v[226:229], v[4:7]
	v_mfma_f32_16x16x32_bf16 v[0:3], v[194:197], v[226:229], v[0:3]
	v_mfma_f32_16x16x32_bf16 v[48:51], v[186:189], v[206:209], v[48:51]
	v_mfma_f32_16x16x32_bf16 v[40:43], v[198:201], v[206:209], v[40:43]
	v_mfma_f32_16x16x32_bf16 v[28:31], v[186:189], v[214:217], v[28:31]
	v_mfma_f32_16x16x32_bf16 v[24:27], v[198:201], v[214:217], v[24:27]
	v_mfma_f32_16x16x32_bf16 v[12:15], v[186:189], v[222:225], v[12:15]
	v_mfma_f32_16x16x32_bf16 v[8:11], v[198:201], v[222:225], v[8:11]
	v_mfma_f32_16x16x32_bf16 v[4:7], v[186:189], v[230:233], v[4:7]
	v_mfma_f32_16x16x32_bf16 v[0:3], v[198:201], v[230:233], v[0:3]
	s_barrier
	s_add_i32 s52, s52, 2
	s_add_u32 s18, s18, 0x100
	s_addc_u32 s19, s19, 0
	s_cmp_gt_u32 s52, 13
	s_cbranch_scc0 .LBB0_586
	s_waitcnt vmcnt(0)
	s_cmpk_lt_u32 s33, 0x100
	s_cbranch_scc0 .LBB0_589
	s_barrier

; #define LAS __attribute__((address_space(3)))
; __device__ __forceinline__ void peer_block(int tok0, float* X1, const unsigned short* X1B, const int* TKI, const float* TKS, __amdgpu_buffer_rsrc_t U8r, __amdgpu_buffer_rsrc_t V6, const float* USC, const float* VSC,
;                                            const float* finw, pw_ptr L, int lane) {
;     const int g = lane >> 3, m = lane & 7, g16 = 16 * g, lo16 = 16 * m, hi8 = NEXP * 128 + 8 * m;
; #pragma unroll
;     for (int t = 0; t < PT; ++t) {
;         const size_t tk = (size_t)(tok0 + t);
;         const size_t rk0 = ((size_t)(lane >> 4) * M + tk) * 16 + (lane & 15), rk1 = rk0 + (size_t)4 * M * 16;
;         *(LAS int*)(L + PW_REC + t * 512 + lane * 4) = TKI[rk0]; *(LAS int*)(L + PW_REC + t * 512 + 256 + lane * 4) = TKI[rk1];
;         *(LAS int*)(L + PW_ACT + t * 512 + lane * 4) = 0; *(LAS int*)(L + PW_ACT + t * 512 + 256 + lane * 4) = 0;
;         const v4u* xb = (const v4u*)(X1B + tk * D + 16 * lane); float ss = 0.f, am = 0.f; float xv[16];
;         const v4u xb0 = xb[0], xb1 = xb[1];
; __global__ void __launch_bounds__(NWAVES * 64, 2) mk_fwd(Params P) {
;     ...
;     if (IN(5)) {
;         const int gw = vcu * NWAVES + wave, NGW = G * NWAVES;
;         const unsigned long long ub_ = (unsigned long long)(uintptr_t)U8, vb_ = (unsigned long long)(uintptr_t)V8;
;         const unsigned long long ubu_ = ((unsigned long long)(unsigned)__builtin_amdgcn_readfirstlane((int)(ub_ >> 32)) << 32) | (unsigned)__builtin_amdgcn_readfirstlane((int)ub_);
;         const unsigned long long vbu_ = ((unsigned long long)(unsigned)__builtin_amdgcn_readfirstlane((int)(vb_ >> 32)) << 32) | (unsigned)__builtin_amdgcn_readfirstlane((int)vb_);
;         const __amdgpu_buffer_rsrc_t U6r = __builtin_amdgcn_make_buffer_rsrc((void*)(uintptr_t)ubu_, 0, NEXP * 1024, 0x00020000), V6r = __builtin_amdgcn_make_buffer_rsrc((void*)(uintptr_t)vbu_, 0, NEXP * 768, 0x00020000);
;         pw_ptr L = (pw_ptr)((LAS char*)lds + wave * PW_BYTES);
;         for (int tok0 = gw * PT; tok0 < M; tok0 += NGW * PT) peer_block(tok0, P.out, X1B, TKI, TKS, U6r, V6r, USC, VSC, P.finw, L, lane);
.LBB0_675:
	s_setprio 0
	s_cmp_lt_i32 s72, 6
	s_cselect_b64 s[0:1], -1, 0
	s_cmp_gt_i32 s73, 5
	s_cselect_b64 s[2:3], -1, 0
	s_and_b64 s[0:1], s[0:1], s[2:3]
	s_andn2_b64 vcc, exec, s[0:1]
	s_cbranch_vccnz .LBB0_745
	v_readlane_b32 s0, v252, 0
	s_lshl_b32 s0, s0, 3
	v_readlane_b32 s1, v252, 9
	s_add_i32 s0, s0, s1
	s_cmpk_gt_i32 s0, 0x1fff
	s_cbranch_scc1 .LBB0_745
	v_mov_b32_e32 v73, 0
	v_lshlrev_b32_e32 v4, 5, v193
	v_mov_b32_e32 v5, v73
	v_lshl_add_u64 v[76:77], s[20:21], 0, v[4:5]
	v_mbcnt_lo_u32_b32 v4, -1, 0
	v_mbcnt_hi_u32_b32 v4, -1, v4
	v_and_b32_e32 v9, 64, v4
	v_xor_b32_e32 v5, 16, v4
	v_add_u32_e32 v9, 64, v9
	v_cmp_lt_i32_e32 vcc, v5, v9
	v_lshlrev_b32_e32 v0, 1, v180
	v_and_b32_e32 v7, 0x70, v0
	v_cndmask_b32_e32 v5, v4, v5, vcc
	v_lshlrev_b32_e32 v88, 2, v5
	v_xor_b32_e32 v5, 32, v4
	v_lshrrev_b32_e32 v0, 4, v193
	v_cmp_lt_i32_e32 vcc, v5, v9
	v_mul_u32_u24_e32 v72, 0xc000, v0
	v_and_b32_e32 v0, 15, v180
	v_cndmask_b32_e32 v4, v4, v5, vcc
	v_lshlrev_b32_e32 v0, 2, v0
	v_mov_b32_e32 v1, v73
	v_lshlrev_b32_e32 v89, 2, v4
	v_and_b32_e32 v4, 2, v180
	v_and_b32_e32 v6, 7, v180
	v_lshl_add_u64 v[74:75], s[6:7], 0, v[0:1]
	v_cmp_eq_u32_e64 s[4:5], 0, v4
	v_and_b32_e32 v4, 1, v180
	v_lshl_add_u64 v[78:79], s[8:9], 0, v[0:1]
	v_mov_b32_e32 v0, 0x200000
	v_readlane_b32 s1, v252, 9
	v_lshlrev_b32_e32 v5, 3, v4
	v_bfe_u32 v9, v180, 1, 2
	v_lshl_or_b32 v92, v6, 3, v0
	v_and_b32_e32 v0, 8, v180
	s_mulk_i32 s1, 0x4840
	v_lshlrev_b32_e32 v2, 4, v193
	v_mov_b32_e32 v3, v73
	v_or3_b32 v10, v5, v9, v7
	v_cmp_eq_u32_e64 s[8:9], 0, v0
	v_and_b32_e32 v0, 56, v180
	s_mov_b32 s63, 0x20000
	s_add_i32 s33, s1, 0
	v_lshlrev_b32_e32 v8, 2, v193
	v_lshlrev_b32_e32 v90, 4, v6
	v_lshlrev_b32_e32 v91, 2, v7
	v_lshlrev_b32_e32 v10, 2, v10
	v_lshl_add_u64 v[80:81], s[56:57], 0, v[2:3]
	v_lshlrev_b32_e32 v82, 3, v193
	v_mov_b32_e32 v83, v73
	v_lshl_add_u64 v[86:87], s[54:55], 0, v[2:3]
	v_or3_b32 v1, v9, v7, v5
	v_mov_b32_e32 v3, 0xc00
	v_lshl_or_b32 v0, v6, 6, v0
	s_mov_b32 s62, 0x1000000
	s_and_b32 s61, s61, 0xffff
	s_mov_b32 s66, 0xc00000
	s_mov_b32 s67, s63
	s_and_b32 s65, s65, 0xffff
	s_mul_i32 s12, s0, 6
	s_waitcnt lgkmcnt(0)
	s_mov_b32 s42, 64
	v_cmp_eq_u32_e64 s[0:1], 0, v193
	v_cmp_gt_u32_e64 s[2:3], 4, v6
	v_cmp_eq_u32_e64 s[6:7], 0, v4
	v_lshl_add_u64 v[84:85], s[20:21], 0, v[82:83]
	s_mul_i32 s43, s90, 48
	v_or_b32_e32 v83, 0x200, v91
	v_lshl_or_b32 v93, v1, 2, v3
	v_add_u32_e32 v94, 0x1840, v90
	v_add_u32_e32 v95, 0x1840, v0
	v_add_u32_e32 v96, s33, v8
	s_mov_b32 s44, 0xda24260
	s_mov_b32 s45, 0x42fe0000
	s_mov_b32 s46, 0x40c0c00
	v_add_u32_e32 v97, s33, v2
	v_mov_b32_e32 v98, 0x358637bd
	s_mov_b32 s47, 0xf800000
	v_mov_b32_e32 v99, 0x260
	s_movk_i32 s48, 0x80
	s_mov_b32 s49, 0xe00000
	v_add_u32_e32 v100, s33, v10
	s_mov_b32 s50, 0x378e98ab
	s_mov_b32 s51, 0x3b7cd369
	s_mov_b32 s52, 0xbcc618b2
	s_mov_b32 s53, 0x3dda74e4
	s_mov_b32 s54, 0x3f228afd
	s_mov_b32 s55, 0x3e03c728
	s_mov_b32 s56, 0xbfb8aa3b
	s_mov_b32 s57, 0x42ce8ed0
	s_mov_b32 s58, 0xc2b17218
	v_mov_b32_e32 v101, 0x3ba10414
	s_brev_b32 s59, -2
	v_mov_b32_e32 v102, 0xb9c68948
	v_mov_b32_e32 v103, 0x7f800000
	s_branch .LBB0_679
